# GDN prep in chunk-major order, 7 whole rounds before barrier + 320 items beside the scans on all sample WGs (per-round counters, write-through records); sample-recurrence LDS swizzle
# speedup vs baseline: 1.0284x; 1.0121x over previous
; __device__ __forceinline__ int fresh_tid() { int t = threadIdx.x; asm volatile("" : "+v"(t)); return t; }
; __device__ __forceinline__ void gdn_prep_load(PrepRaw& R, int item, int b0, const bf16_t* qkv, const float* bg, int tid) {
;     const int h = item & 7, c = (item >> 3) % NCHUNK, b = b0 + (item >> 3) / NCHUNK;
;     const int tbase = 64 * c - 48, cc = tid & 15, i0 = (tid >> 4) * 2;
; #pragma unroll
;     for (int part = 0; part < 2; ++part)
; #pragma unroll
;         for (int j = 0; j < 5; ++j) { const int t = tbase + i0 - 3 + j;
;             R.x[part][j] = (t >= 0) ? *(const u32x4*)(qkv + (size_t)(b * LP + t) * CONVCH + part * 1024 + h * 128 + 8 * cc) : (u32x4){0u, 0u, 0u, 0u}; }
; __device__ __forceinline__ void gdn_all(LAS unsigned char* lds, const XcdBarrier& xbar, const int G, const int bx, unsigned char* ws, float* out, const bf16_t* qkv, const float* bg, const float* gconv_w, ...
;     const int nfull = NITEM_P / G, nlate = NITEM_P - nfull * G;
;     unsigned* late_cnt = (unsigned*)(ws + WS_CTL) + 8192 + 1024;
;     {
;         { PrepRaw R; if (nfull > 0) gdn_prep_load(R, bx, 0, qkv, bg, fresh_tid());
.LBB0_435:
	s_or_b64 exec, exec, s[0:1]
	s_abs_i32 s53, s96
	s_waitcnt lgkmcnt(0)
	v_cvt_f32_u32_e32 v1, s53
	s_sub_i32 s0, 0, s53
	s_barrier
	v_rcp_iflag_f32_e32 v1, v1
	s_nop 0
	v_mul_f32_e32 v1, 0x4f7ffffe, v1
	v_cvt_u32_f32_e32 v1, v1
	s_nop 0
	v_readfirstlane_b32 s56, v1
	s_mul_i32 s0, s0, s56
	s_mul_hi_u32 s0, s56, s0
	s_add_i32 s56, s56, s0
	s_mul_hi_u32 s0, s56, 0x840
	s_mul_i32 s1, s0, s53
	s_sub_i32 s1, 0x840, s1
	s_add_i32 s2, s0, 1
	s_sub_i32 s3, s1, s53
	s_cmp_ge_u32 s1, s53
	s_cselect_b32 s0, s2, s0
	s_cselect_b32 s1, s3, s1
	s_add_i32 s2, s0, 1
	s_cmp_ge_u32 s1, s53
	s_cselect_b32 s0, s2, s0
	v_readlane_b32 s1, v245, 35
	s_xor_b32 s0, s0, s1
	s_sub_i32 s3, s0, s1
	s_mov_b32 s3, 7
	s_cmp_gt_i32 s3, 0
	s_cselect_b64 s[14:15], -1, 0
	s_cmp_lt_i32 s3, 1
	s_cbranch_scc1 .LBB0_461
	s_and_b32 s100, s94, 7
	s_lshr_b32 s101, s94, 3
	s_and_b32 s98, s101, 7
	s_lshr_b32 s101, s101, 3
	s_mul_i32 s98, s98, 33
	s_add_i32 s98, s98, s101
	s_lshl_b32 s98, s98, 3
	s_or_b32 s99, s98, s100
	s_ashr_i32 s0, s99, 3
	s_mul_hi_i32 s1, s0, 0x3e0f83e1
	s_lshr_b32 s4, s1, 31
	s_ashr_i32 s1, s1, 3
	s_add_i32 s18, s1, s4
	s_mul_i32 s1, s18, 33
	v_mov_b32_e32 v1, v0
	s_sub_i32 s0, s0, s1
	s_lshl_b32 s19, s0, 6
	v_ashrrev_i32_e32 v2, 3, v1
	s_and_b32 s2, s99, 7
	v_and_b32_e32 v2, -2, v2
	s_sub_i32 s0, s19, 51
	v_add_u32_e32 v18, s0, v2
	s_lshl_b32 s0, s2, 8
	s_add_u32 s0, s88, s0
	v_lshlrev_b32_e32 v2, 4, v1
	v_mov_b32_e32 v3, 0
	s_addc_u32 s1, s89, 0
	v_and_b32_e32 v2, 0xf0, v2
	v_mov_b32_e32 v4, v3
	v_mov_b32_e32 v5, v3
	s_mulk_i32 s18, 0x810
	v_lshl_add_u64 v[34:35], s[0:1], 0, v[2:3]
	v_mov_b32_e32 v2, v3
	v_mov_b64_e32 v[8:9], v[4:5]
	v_cmp_lt_i32_e32 vcc, -1, v18
	v_add_u32_e32 v26, s18, v18
	v_mov_b64_e32 v[6:7], v[2:3]
	s_and_saveexec_b64 s[0:1], vcc
	s_cbranch_execz .LBB0_438
	s_movk_i32 s4, 0x1800
	v_mad_i64_i32 v[6:7], s[4:5], v26, s4, v[34:35]
	global_load_dwordx4 v[6:9], v[6:7], off

; __device__ __forceinline__ void gdn_prep_item(LAS unsigned char* lds, int item, int b0, PrepRaw& R, int next_item, const bf16_t* qkv, const float* bg, const float* gconv_w, unsigned char* rec, float* gtarr) {
;     ...
;     { const int c = (item >> 3) % NCHUNK, b = b0 + (item >> 3) / NCHUNK, tbase = 64 * c - 48, cc = tid & 15, i0 = (tid >> 4) * 2;
; #pragma unroll
;       for (int j = 0; j < 5; ++j) { const int t = tbase + i0 - 3 + j; xv[j] = (t >= 0) ? *(const u32x4*)(qkv + (size_t)(b * LP + t) * CONVCH + 2048 + h * 128 + 8 * cc) : (u32x4){0u, 0u, 0u, 0u}; } }
; __device__ __forceinline__ void gdn_all(LAS unsigned char* lds, const XcdBarrier& xbar, const int G, const int bx, unsigned char* ws, float* out, const bf16_t* qkv, const float* bg, const float* gconv_w, ...
;     ...
;           for (int k = 0; k < nfull; ++k) { const int item = bx + k * G; gdn_prep_item(lds, item, 0, R, k + 1 < nfull ? item + G : -1, qkv, bg, gconv_w, gdn_rec(ws, out, item), gtarr); } }
.LBB0_465:
	s_mul_i32 s0, s29, s96
	s_add_i32 s18, s0, s94
	s_mov_b32 s99, s18
	s_and_b32 s100, s18, 7
	s_lshr_b32 s101, s18, 3
	s_and_b32 s98, s101, 7
	s_lshr_b32 s101, s101, 3
	s_mul_i32 s98, s98, 33
	s_add_i32 s98, s98, s101
	s_lshl_b32 s98, s98, 3
	s_or_b32 s18, s98, s100
	s_ashr_i32 s0, s18, 3
	s_mul_hi_i32 s1, s0, 0x3e0f83e1
	v_mov_b32_e32 v116, v0
	s_lshr_b32 s4, s1, 31
	s_ashr_i32 s1, s1, 3
	s_add_i32 s4, s1, s4
	v_ashrrev_i32_e32 v115, 3, v116
	s_mul_i32 s1, s4, 33
	v_and_b32_e32 v95, -2, v115
	v_and_b32_e32 v114, 15, v116
	s_sub_i32 s0, s0, s1
	v_subrev_u32_e32 v119, 51, v95
	v_ashrrev_i32_e32 v117, 6, v116
	v_lshl_add_u32 v66, s0, 6, v119
	s_lshl_b32 s0, s18, 7
	v_lshlrev_b32_e32 v94, 3, v114
	v_readfirstlane_b32 s30, v117
	s_mulk_i32 s4, 0x810
	s_and_b32 s6, s0, 0x380
	v_cmp_lt_i32_e32 vcc, -1, v66
	v_lshlrev_b32_e32 v36, 1, v94
	v_mov_b32_e32 v46, 0
	v_mov_b32_e32 v47, 0
	v_mov_b32_e32 v48, 0
	v_mov_b32_e32 v49, 0
	s_and_saveexec_b64 s[0:1], vcc
	s_cbranch_execz .LBB0_467
	v_add_u32_e32 v37, s4, v66
	v_mov_b64_e32 v[46:47], s[88:89]
	v_mad_i64_i32 v[46:47], s[8:9], v37, s2, v[46:47]
	s_lshl_b32 s14, s6, 1
	v_lshl_add_u64 v[46:47], v[46:47], 0, s[14:15]
	v_mov_b32_e32 v37, v34
	v_lshl_add_u64 v[46:47], v[46:47], 0, v[36:37]
	v_add_co_u32_e32 v46, vcc, 0x1000, v46
	s_nop 1
	v_addc_co_u32_e32 v47, vcc, 0, v47, vcc
	global_load_dwordx4 v[46:49], v[46:47], off

; __device__ __forceinline__ float silu_f(float x) { return x * __builtin_amdgcn_rcpf(1.0f + __expf(-x)); }
; __device__ __forceinline__ void gdn_prep_item(LAS unsigned char* lds, int item, int b0, PrepRaw& R, int next_item, const bf16_t* qkv, const float* bg, const float* gconv_w, unsigned char* rec, float* gtarr) {
;     ...
;     {
;         const int cc = tid & 15, i0 = (tid >> 4) * 2;
;         const float be0 = Bs[i0], be1 = Bs[i0 + 1], eg0 = EG[i0], eg1 = EG[i0 + 1];
; #pragma unroll
;         for (int part = 0; part < 3; ++part) {
;             const int col = part * 1024 + h * 128 + 8 * cc;
;             float y0[8], y1[8];
; #pragma unroll
;             for (int e = 0; e < 8; ++e) { y0[e] = 0.f; y1[e] = 0.f; }
; #pragma unroll
;             for (int j = 0; j < 5; ++j) { const u32x4 v = part < 2 ? R.x[part < 2 ? part : 0][j] : xv[j]; const unsigned vv[4] = {v.x, v.y, v.z, v.w}; float x[8];
; #pragma unroll
;                 for (int e = 0; e < 4; ++e) { x[2 * e] = __uint_as_float(vv[e] << 16); x[2 * e + 1] = __uint_as_float(vv[e] & 0xffff0000u); }
;                 if (j < 4) { const f32x4 wa = *(const f32x4*)(gconv_w + j * CONVCH + col), wb = *(const f32x4*)(gconv_w + j * CONVCH + col + 4);
; #pragma unroll
;                     for (int e = 0; e < 8; ++e) y0[e] += (e < 4 ? wa[e] : wb[e - 4]) * x[e]; }
;                 if (j > 0) { const f32x4 wa = *(const f32x4*)(gconv_w + (j - 1) * CONVCH + col), wb = *(const f32x4*)(gconv_w + (j - 1) * CONVCH + col + 4);
; #pragma unroll
;                     for (int e = 0; e < 8; ++e) y1[e] += (e < 4 ? wa[e] : wb[e - 4]) * x[e]; } }
;             float s0 = 0.f, s1 = 0.f;
; #pragma unroll
;             for (int e = 0; e < 8; ++e) { y0[e] = silu_f(y0[e]); y1[e] = silu_f(y1[e]); s0 += y0[e] * y0[e]; s1 += y1[e] * y1[e]; }
.LBB0_482:
	s_or_b64 exec, exec, s[0:1]
	v_or_b32_e32 v36, s6, v94
	v_lshlrev_b32_e32 v36, 2, v36
	v_mov_b32_e32 v37, v34
	v_lshl_add_u64 v[98:99], s[72:73], 0, v[36:37]
	s_mov_b64 s[0:1], 0x3000
	s_waitcnt lgkmcnt(0)
	s_barrier
	global_load_dwordx4 v[82:85], v36, s[72:73] offset:16
	global_load_dwordx4 v[66:69], v36, s[72:73]
	v_lshl_add_u64 v[36:37], v[98:99], 0, s[0:1]
	s_mov_b64 s[0:1], 0x6000
	v_lshl_add_u64 v[70:71], v[98:99], 0, s[0:1]
	s_mov_b64 s[0:1], 0x9000
	global_load_dwordx4 v[86:89], v[36:37], off offset:16
	global_load_dwordx4 v[90:93], v[70:71], off offset:16
	v_lshl_add_u64 v[36:37], v[98:99], 0, s[0:1]
	global_load_dwordx4 v[120:123], v[36:37], off offset:16
	s_movk_i32 s0, 0x4000
	v_add_co_u32_e32 v100, vcc, s0, v98
	s_movk_i32 s0, 0x7000
	s_nop 0
	v_addc_co_u32_e32 v101, vcc, 0, v99, vcc
	v_add_co_u32_e32 v102, vcc, s0, v98
	s_mov_b32 s0, 0xa000
	s_nop 0
	v_addc_co_u32_e32 v103, vcc, 0, v99, vcc
	v_add_co_u32_e32 v104, vcc, s0, v98
	global_load_dwordx4 v[70:73], v[100:101], off offset:-4096
	global_load_dwordx4 v[74:77], v[102:103], off offset:-4096
	v_addc_co_u32_e32 v105, vcc, 0, v99, vcc
	global_load_dwordx4 v[78:81], v[104:105], off offset:-4096
	s_waitcnt vmcnt(8)
	v_lshlrev_b32_e32 v132, 16, v4
	v_and_b32_e32 v133, 0xffff0000, v4
	v_lshlrev_b32_e32 v134, 16, v12
	v_and_b32_e32 v135, 0xffff0000, v12
	v_lshlrev_b32_e32 v136, 16, v16
	v_and_b32_e32 v137, 0xffff0000, v16
	v_lshlrev_b32_e32 v138, 16, v20
	v_and_b32_e32 v139, 0xffff0000, v20
	v_lshlrev_b32_e32 v140, 16, v3
	v_and_b32_e32 v141, 0xffff0000, v3
	v_lshlrev_b32_e32 v142, 16, v11
	v_and_b32_e32 v143, 0xffff0000, v11
	v_lshlrev_b32_e32 v144, 16, v15
	v_and_b32_e32 v145, 0xffff0000, v15
	v_lshlrev_b32_e32 v154, 16, v2
	v_and_b32_e32 v155, 0xffff0000, v2
	v_lshlrev_b32_e32 v158, 16, v10
	v_and_b32_e32 v159, 0xffff0000, v10
	v_lshlrev_b32_e32 v160, 16, v14
	v_and_b32_e32 v161, 0xffff0000, v14
	v_lshlrev_b32_e32 v162, 16, v18
	v_and_b32_e32 v163, 0xffff0000, v18
	s_add_i32 s29, s29, 1
	s_add_i32 s0, s99, s96
	s_and_b32 s100, s0, 7
	s_lshr_b32 s101, s0, 3
	s_and_b32 s98, s101, 7
	s_lshr_b32 s101, s101, 3
	s_mul_i32 s98, s98, 33
	s_add_i32 s98, s98, s101
	s_lshl_b32 s98, s98, 3
	s_or_b32 s0, s98, s100
	v_or_b32_e32 v164, 1, v115
	s_cmp_lt_i32 s29, s3
	v_lshlrev_b32_e32 v36, 2, v95
	v_lshlrev_b32_e32 v37, 2, v164
	s_cselect_b32 s14, s0, -1
	s_add_i32 s0, 0, 0x1d100
	s_add_i32 s31, 0, 0x1d200
	v_lshlrev_b32_e32 v124, 16, v5
	v_and_b32_e32 v125, 0xffff0000, v5
	v_add_u32_e32 v96, s0, v36
	v_add_u32_e32 v97, s0, v37
	v_add_u32_e32 v146, s31, v36
	v_add_u32_e32 v147, s31, v37
	ds_read_b32 v36, v96
	ds_read_b32 v37, v97
	ds_read_b32 v96, v146
	ds_read_b32 v97, v147
	v_lshlrev_b32_e32 v126, 16, v13
	v_and_b32_e32 v127, 0xffff0000, v13
	v_lshlrev_b32_e32 v128, 16, v17
	v_and_b32_e32 v129, 0xffff0000, v17
	v_lshlrev_b32_e32 v130, 16, v21
	v_and_b32_e32 v131, 0xffff0000, v21
	s_waitcnt vmcnt(7)
	v_pk_fma_f32 v[148:149], v[82:83], v[132:133], 0 op_sel_hi:[1,1,0]
	s_waitcnt vmcnt(6)
	v_pk_fma_f32 v[150:151], v[68:69], v[140:141], 0 op_sel_hi:[1,1,0]
	v_pk_fma_f32 v[156:157], v[66:67], v[154:155], 0 op_sel_hi:[1,1,0]
	v_pk_fma_f32 v[146:147], v[84:85], v[124:125], 0 op_sel_hi:[1,1,0]
	s_waitcnt vmcnt(5)
	v_pk_fma_f32 v[148:149], v[86:87], v[134:135], v[148:149]
	s_waitcnt vmcnt(4)
	v_pk_fma_f32 v[148:149], v[90:91], v[136:137], v[148:149]
	v_pk_fma_f32 v[146:147], v[88:89], v[126:127], v[146:147]
	s_waitcnt vmcnt(3)
	v_pk_fma_f32 v[138:139], v[120:121], v[138:139], v[148:149]
	v_pk_fma_f32 v[146:147], v[92:93], v[128:129], v[146:147]
	v_mul_f32_e32 v148, 0xbfb8aa3b, v138
	v_mul_f32_e32 v149, 0xbfb8aa3b, v139
	v_exp_f32_e32 v148, v148
	v_exp_f32_e32 v149, v149
	v_pk_fma_f32 v[130:131], v[122:123], v[130:131], v[146:147]
	v_add_f32_e32 v148, 1.0, v148
	v_add_f32_e32 v149, 1.0, v149
	v_rcp_f32_e32 v148, v148
	v_rcp_f32_e32 v149, v149
	v_mul_f32_e32 v146, 0xbfb8aa3b, v130
	s_waitcnt vmcnt(2)
	v_pk_fma_f32 v[150:151], v[72:73], v[142:143], v[150:151]
	v_pk_fma_f32 v[156:157], v[70:71], v[158:159], v[156:157]
	s_waitcnt vmcnt(1)
	v_pk_fma_f32 v[150:151], v[76:77], v[144:145], v[150:151]
	v_pk_mul_f32 v[138:139], v[138:139], v[148:149]
	v_lshlrev_b32_e32 v148, 16, v19
	v_and_b32_e32 v149, 0xffff0000, v19
	s_waitcnt vmcnt(0)
; __device__ __forceinline__ float silu_f(float x) { return x * __builtin_amdgcn_rcpf(1.0f + __expf(-x)); }
; __device__ __forceinline__ void gdn_prep_item(LAS unsigned char* lds, int item, int b0, PrepRaw& R, int next_item, const bf16_t* qkv, const float* bg, const float* gconv_w, unsigned char* rec, float* gtarr) {
;     ...
;             for (int j = 0; j < 5; ++j) { const u32x4 v = part < 2 ? R.x[part < 2 ? part : 0][j] : xv[j]; const unsigned vv[4] = {v.x, v.y, v.z, v.w}; float x[8];
; #pragma unroll
;                 for (int e = 0; e < 4; ++e) { x[2 * e] = __uint_as_float(vv[e] << 16); x[2 * e + 1] = __uint_as_float(vv[e] & 0xffff0000u); }
;                 if (j < 4) { const f32x4 wa = *(const f32x4*)(gconv_w + j * CONVCH + col), wb = *(const f32x4*)(gconv_w + j * CONVCH + col + 4);
; #pragma unroll
;                     for (int e = 0; e < 8; ++e) y0[e] += (e < 4 ? wa[e] : wb[e - 4]) * x[e]; }
;                 if (j > 0) { const f32x4 wa = *(const f32x4*)(gconv_w + (j - 1) * CONVCH + col), wb = *(const f32x4*)(gconv_w + (j - 1) * CONVCH + col + 4);
; #pragma unroll
;                     for (int e = 0; e < 8; ++e) y1[e] += (e < 4 ? wa[e] : wb[e - 4]) * x[e]; } }
;             float s0 = 0.f, s1 = 0.f;
; #pragma unroll
;             for (int e = 0; e < 8; ++e) { y0[e] = silu_f(y0[e]); y1[e] = silu_f(y1[e]); s0 += y0[e] * y0[e]; s1 += y1[e] * y1[e]; }
;             if (part < 2) {
;                 s0 = row16_sum(s0); s1 = row16_sum(s1);
;                 float sc0 = rsqrtf(s0 + EPS), sc1 = rsqrtf(s1 + EPS); if (part == 0) { sc0 *= 0.08838834764831845f; sc1 *= 0.08838834764831845f; }
; #pragma unroll
;                 for (int e = 0; e < 8; ++e) { y0[e] *= sc0; y1[e] *= sc1; }
	v_pk_fma_f32 v[148:149], v[80:81], v[148:149], v[150:151]
	v_pk_fma_f32 v[156:157], v[74:75], v[160:161], v[156:157]
	v_mul_f32_e32 v150, 0xbfb8aa3b, v148
	v_exp_f32_e32 v152, v150
	v_mul_f32_e32 v150, 0xbfb8aa3b, v149
	v_exp_f32_e32 v153, v150
	v_pk_fma_f32 v[156:157], v[78:79], v[162:163], v[156:157]
	v_add_f32_e32 v152, 1.0, v152
	v_mul_f32_e32 v162, 0xbfb8aa3b, v156
	v_add_f32_e32 v153, 1.0, v153
	v_mul_f32_e32 v163, 0xbfb8aa3b, v157
	v_rcp_f32_e32 v152, v152
	v_rcp_f32_e32 v153, v153
	v_exp_f32_e32 v162, v162
	v_exp_f32_e32 v163, v163
	v_mul_f32_e32 v147, 0xbfb8aa3b, v131
	v_pk_mul_f32 v[148:149], v[148:149], v[152:153]
	v_add_f32_e32 v152, 1.0, v162
	v_add_f32_e32 v153, 1.0, v163
	v_lshlrev_b32_e32 v162, 16, v9
	v_and_b32_e32 v163, 0xffff0000, v9
	v_pk_fma_f32 v[84:85], v[84:85], v[162:163], 0 op_sel_hi:[1,1,0]
	v_exp_f32_e32 v146, v146
	v_pk_fma_f32 v[84:85], v[88:89], v[124:125], v[84:85]
	v_exp_f32_e32 v147, v147
	v_pk_fma_f32 v[84:85], v[92:93], v[126:127], v[84:85]
	v_rcp_f32_e32 v152, v152
	v_pk_fma_f32 v[84:85], v[122:123], v[128:129], v[84:85]
	v_rcp_f32_e32 v153, v153
	v_mul_f32_e32 v88, 0xbfb8aa3b, v84
	v_mul_f32_e32 v89, 0xbfb8aa3b, v85
	v_exp_f32_e32 v88, v88
	v_exp_f32_e32 v89, v89
	v_add_f32_e32 v146, 1.0, v146
	v_add_f32_e32 v147, 1.0, v147
	v_add_f32_e32 v88, 1.0, v88
	v_add_f32_e32 v89, 1.0, v89
	v_rcp_f32_e32 v88, v88
	v_rcp_f32_e32 v89, v89
	v_pk_mul_f32 v[122:123], v[156:157], v[152:153]
	v_rcp_f32_e32 v146, v146
	v_rcp_f32_e32 v147, v147
	v_pk_mul_f32 v[84:85], v[84:85], v[88:89]
	v_lshlrev_b32_e32 v88, 16, v8
	v_and_b32_e32 v89, 0xffff0000, v8
	v_pk_fma_f32 v[82:83], v[82:83], v[88:89], 0 op_sel_hi:[1,1,0]
	v_pk_mul_f32 v[124:125], v[122:123], v[122:123]
	v_pk_fma_f32 v[82:83], v[86:87], v[132:133], v[82:83]
	v_pk_mul_f32 v[92:93], v[148:149], v[148:149]
	v_pk_fma_f32 v[82:83], v[90:91], v[134:135], v[82:83]
	v_lshlrev_b32_e32 v90, 16, v7
	v_and_b32_e32 v91, 0xffff0000, v7
	v_pk_fma_f32 v[68:69], v[68:69], v[90:91], 0 op_sel_hi:[1,1,0]
	v_pk_fma_f32 v[82:83], v[120:121], v[136:137], v[82:83]
	v_pk_fma_f32 v[68:69], v[72:73], v[140:141], v[68:69]
	v_mul_f32_e32 v86, 0xbfb8aa3b, v82
	v_pk_fma_f32 v[68:69], v[76:77], v[142:143], v[68:69]
	v_exp_f32_e32 v88, v86
	v_pk_fma_f32 v[68:69], v[80:81], v[144:145], v[68:69]
	v_lshlrev_b32_e32 v80, 16, v6
	v_and_b32_e32 v81, 0xffff0000, v6
	v_pk_fma_f32 v[66:67], v[66:67], v[80:81], 0 op_sel_hi:[1,1,0]
	v_mul_f32_e32 v72, 0xbfb8aa3b, v68
	v_pk_fma_f32 v[66:67], v[70:71], v[154:155], v[66:67]
	v_exp_f32_e32 v76, v72
	v_pk_fma_f32 v[66:67], v[74:75], v[158:159], v[66:67]
	v_mul_f32_e32 v72, 0xbfb8aa3b, v69
	v_pk_fma_f32 v[66:67], v[78:79], v[160:161], v[66:67]
	v_exp_f32_e32 v77, v72
	v_mul_f32_e32 v70, 0xbfb8aa3b, v66
	v_mul_f32_e32 v71, 0xbfb8aa3b, v67
	v_exp_f32_e32 v70, v70
	v_exp_f32_e32 v71, v71
	v_mul_f32_e32 v86, 0xbfb8aa3b, v83
	v_exp_f32_e32 v89, v86
	v_add_f32_e32 v70, 1.0, v70
	v_add_f32_e32 v71, 1.0, v71
	v_add_f32_e32 v76, 1.0, v76
	v_add_f32_e32 v77, 1.0, v77
	v_rcp_f32_e32 v70, v70
	v_rcp_f32_e32 v71, v71
	v_rcp_f32_e32 v76, v76
	v_rcp_f32_e32 v77, v77
	v_add_f32_e32 v88, 1.0, v88
	v_add_f32_e32 v89, 1.0, v89
	v_rcp_f32_e32 v88, v88
	v_rcp_f32_e32 v89, v89
	v_pk_mul_f32 v[66:67], v[66:67], v[70:71]
	v_pk_mul_f32 v[68:69], v[68:69], v[76:77]
	v_pk_mul_f32 v[70:71], v[66:67], v[66:67]
	v_pk_mul_f32 v[76:77], v[68:69], v[68:69]
	v_mov_b32_e32 v78, v124
	v_mov_b32_e32 v79, v70
	v_mov_b32_e32 v70, v125
	v_pk_mul_f32 v[72:73], v[82:83], v[88:89]
	v_pk_add_f32 v[70:71], v[78:79], v[70:71]
	v_mov_b32_e32 v78, v92
	v_mov_b32_e32 v79, v76
	v_pk_mul_f32 v[150:151], v[138:139], v[138:139]
	v_pk_mul_f32 v[74:75], v[72:73], v[72:73]
	v_pk_add_f32 v[70:71], v[78:79], v[70:71]
	v_mov_b32_e32 v76, v93
	v_pk_mul_f32 v[130:131], v[130:131], v[146:147]
	v_pk_add_f32 v[70:71], v[76:77], v[70:71]
	v_mov_b32_e32 v76, v150
	v_mov_b32_e32 v77, v74
	v_pk_mul_f32 v[146:147], v[130:131], v[130:131]
	v_pk_mul_f32 v[86:87], v[84:85], v[84:85]
	v_pk_add_f32 v[70:71], v[76:77], v[70:71]
	v_mov_b32_e32 v74, v151
	v_pk_add_f32 v[70:71], v[74:75], v[70:71]
	v_mov_b32_e32 v74, v146
	v_mov_b32_e32 v75, v86
	v_pk_add_f32 v[70:71], v[74:75], v[70:71]
	v_mov_b32_e32 v86, v147
	v_pk_add_f32 v[70:71], v[86:87], v[70:71]
	v_mov_b32_e32 v74, v34
	v_mov_b32_e32 v75, v34
	v_mad_u64_u32 v[76:77], s[0:1], v164, s23, v[94:95]
	v_mov_b32_dpp v74, v70 quad_perm:[1,0,3,2] row_mask:0xf bank_mask:0xf
	v_mov_b32_dpp v75, v71 quad_perm:[1,0,3,2] row_mask:0xf bank_mask:0xf
	v_pk_add_f32 v[70:71], v[70:71], v[74:75]
	v_mov_b32_e32 v74, v34
	v_mov_b32_e32 v75, v34
	v_lshl_add_u32 v160, v76, 1, 0
	v_mov_b32_dpp v74, v70 quad_perm:[2,3,0,1] row_mask:0xf bank_mask:0xf
	v_mov_b32_dpp v75, v71 quad_perm:[2,3,0,1] row_mask:0xf bank_mask:0xf
	v_pk_add_f32 v[70:71], v[70:71], v[74:75]
	v_mov_b32_e32 v74, v34
	v_mov_b32_e32 v75, v34
	s_nop 0
	v_mov_b32_dpp v74, v70 row_ror:4 row_mask:0xf bank_mask:0xf
	v_mov_b32_dpp v75, v71 row_ror:4 row_mask:0xf bank_mask:0xf
	v_pk_add_f32 v[70:71], v[70:71], v[74:75]
	v_mov_b32_e32 v74, v34
	v_mov_b32_e32 v75, v34
	s_nop 0
	v_mov_b32_dpp v74, v70 row_ror:8 row_mask:0xf bank_mask:0xf
	v_mov_b32_dpp v75, v71 row_ror:8 row_mask:0xf bank_mask:0xf
	v_pk_add_f32 v[70:71], v[70:71], v[74:75]
	s_nop 0
	v_pk_add_f32 v[70:71], v[70:71], s[16:17] op_sel_hi:[1,0]
	s_nop 0
	v_mul_f32_e32 v74, 0x4b800000, v70
	v_cmp_gt_f32_e32 vcc, s24, v70
	s_nop 1
	v_cndmask_b32_e32 v70, v70, v74, vcc
	v_rsq_f32_e32 v70, v70
	v_mad_u64_u32 v[74:75], s[0:1], v95, s23, v[94:95]
	v_lshl_add_u32 v94, v74, 1, 0
	v_mul_f32_e32 v75, 0x45800000, v70
	v_cndmask_b32_e32 v70, v70, v75, vcc
	v_mul_f32_e32 v70, 0x3db504f3, v70
; #define LAS __attribute__((address_space(3)))
; __device__ __forceinline__ unsigned cvt_pk_bf16(float lo, float hi) { const bf16x2_t r = __builtin_convertvector((f32x2){lo, hi}, bf16x2_t); return __builtin_bit_cast(unsigned, r); }
; __device__ __forceinline__ void gdn_prep_item(LAS unsigned char* lds, int item, int b0, PrepRaw& R, int next_item, const bf16_t* qkv, const float* bg, const float* gconv_w, unsigned char* rec, float* gtarr) {
;     ...
;             for (int j = 0; j < 5; ++j) { const u32x4 v = part < 2 ? R.x[part < 2 ? part : 0][j] : xv[j]; const unsigned vv[4] = {v.x, v.y, v.z, v.w}; float x[8];
; #pragma unroll
;                 for (int e = 0; e < 4; ++e) { x[2 * e] = __uint_as_float(vv[e] << 16); x[2 * e + 1] = __uint_as_float(vv[e] & 0xffff0000u); }
;                 if (j < 4) { const f32x4 wa = *(const f32x4*)(gconv_w + j * CONVCH + col), wb = *(const f32x4*)(gconv_w + j * CONVCH + col + 4);
; #pragma unroll
;                     for (int e = 0; e < 8; ++e) y0[e] += (e < 4 ? wa[e] : wb[e - 4]) * x[e]; }
;                 if (j > 0) { const f32x4 wa = *(const f32x4*)(gconv_w + (j - 1) * CONVCH + col), wb = *(const f32x4*)(gconv_w + (j - 1) * CONVCH + col + 4);
; #pragma unroll
;                     for (int e = 0; e < 8; ++e) y1[e] += (e < 4 ? wa[e] : wb[e - 4]) * x[e]; } }
;             float s0 = 0.f, s1 = 0.f;
; #pragma unroll
;             for (int e = 0; e < 8; ++e) { y0[e] = silu_f(y0[e]); y1[e] = silu_f(y1[e]); s0 += y0[e] * y0[e]; s1 += y1[e] * y1[e]; }
;             if (part < 2) {
;                 s0 = row16_sum(s0); s1 = row16_sum(s1);
;                 float sc0 = rsqrtf(s0 + EPS), sc1 = rsqrtf(s1 + EPS); if (part == 0) { sc0 *= 0.08838834764831845f; sc1 *= 0.08838834764831845f; }
; #pragma unroll
;                 for (int e = 0; e < 8; ++e) { y0[e] *= sc0; y1[e] *= sc1; }
;                 LAS unsigned char* img = lds + (part == 0 ? P2_QN : P2_KN);
;                 u32x4 w0, w1; w0.x = cvt_pk_bf16(y0[0], y0[1]); w0.y = cvt_pk_bf16(y0[2], y0[3]); w0.z = cvt_pk_bf16(y0[4], y0[5]); w0.w = cvt_pk_bf16(y0[6], y0[7]);
;                 w1.x = cvt_pk_bf16(y1[0], y1[1]); w1.y = cvt_pk_bf16(y1[2], y1[3]); w1.z = cvt_pk_bf16(y1[4], y1[5]); w1.w = cvt_pk_bf16(y1[6], y1[7]);
;                 *(LAS u32x4*)(img + (i0 * 136 + 8 * cc) * 2) = w0; *(LAS u32x4*)(img + ((i0 + 1) * 136 + 8 * cc) * 2) = w1;
	v_mul_f32_e32 v75, 0x4b800000, v71
	v_cmp_gt_f32_e32 vcc, s24, v71
	v_pk_mul_f32 v[78:79], v[122:123], v[70:71] op_sel_hi:[1,0]
	s_nop 0
	v_cndmask_b32_e32 v71, v71, v75, vcc
	v_rsq_f32_e32 v71, v71
	s_nop 0
	v_pk_mul_f32 v[80:81], v[148:149], v[70:71] op_sel_hi:[1,0]
	v_pk_mul_f32 v[82:83], v[138:139], v[70:71] op_sel_hi:[1,0]
	v_pk_mul_f32 v[86:87], v[130:131], v[70:71] op_sel_hi:[1,0]
	v_mul_f32_e32 v70, 0x45800000, v71
	v_cndmask_b32_e32 v70, v71, v70, vcc
	v_mul_f32_e32 v70, 0x3db504f3, v70
	v_pk_mul_f32 v[66:67], v[66:67], v[70:71] op_sel_hi:[1,0]
	v_pk_mul_f32 v[68:69], v[68:69], v[70:71] op_sel_hi:[1,0]
	v_pk_mul_f32 v[72:73], v[72:73], v[70:71] op_sel_hi:[1,0]
	v_pk_mul_f32 v[70:71], v[84:85], v[70:71] op_sel_hi:[1,0]
	v_cvt_pk_bf16_f32 v66, v66, v67
	v_cvt_pk_bf16_f32 v67, v68, v69
	v_cvt_pk_bf16_f32 v68, v72, v73
	v_cvt_pk_bf16_f32 v69, v70, v71
	v_cvt_pk_bf16_f32 v70, v78, v79
	v_cvt_pk_bf16_f32 v71, v80, v81
	v_cvt_pk_bf16_f32 v72, v82, v83
	v_cvt_pk_bf16_f32 v73, v86, v87
	ds_write_b128 v94, v[66:69]
	ds_write_b128 v160, v[70:73]
	s_mov_b64 s[0:1], 0x1000
	v_lshl_add_u64 v[66:67], v[98:99], 0, s[0:1]
	s_movk_i32 s0, 0x2000
	v_add_co_u32_e32 v82, vcc, s0, v98
	s_mov_b64 s[0:1], 0x4000
	s_nop 0
	v_addc_co_u32_e32 v83, vcc, 0, v99, vcc
	global_load_dwordx4 v[84:87], v[66:67], off offset:16
	v_lshl_add_u64 v[70:71], v[98:99], 0, s[0:1]
	global_load_dwordx4 v[66:69], v[82:83], off offset:-4096
	s_mov_b64 s[0:1], 0x7000
	global_load_dwordx4 v[88:91], v[70:71], off offset:16
	s_nop 0
	global_load_dwordx4 v[70:73], v[100:101], off
	v_lshl_add_u64 v[74:75], v[98:99], 0, s[0:1]
	s_mov_b64 s[0:1], 0xa000
	global_load_dwordx4 v[120:123], v[74:75], off offset:16
	s_nop 0
	global_load_dwordx4 v[74:77], v[102:103], off
	v_lshl_add_u64 v[78:79], v[98:99], 0, s[0:1]
	global_load_dwordx4 v[100:103], v[78:79], off offset:16
	s_nop 0
	global_load_dwordx4 v[78:81], v[104:105], off
	v_lshlrev_b32_e32 v136, 16, v27
	v_and_b32_e32 v137, 0xffff0000, v27
	v_lshlrev_b32_e32 v138, 16, v31
	v_and_b32_e32 v139, 0xffff0000, v31
	v_lshlrev_b32_e32 v140, 16, v39
	v_and_b32_e32 v141, 0xffff0000, v39
	v_lshlrev_b32_e32 v142, 16, v43
	v_and_b32_e32 v143, 0xffff0000, v43
	v_lshlrev_b32_e32 v144, 16, v26
	v_and_b32_e32 v145, 0xffff0000, v26
	v_lshlrev_b32_e32 v146, 16, v30
	v_and_b32_e32 v147, 0xffff0000, v30
	v_lshlrev_b32_e32 v148, 16, v38
	v_and_b32_e32 v149, 0xffff0000, v38
	v_lshlrev_b32_e32 v150, 16, v42
	v_and_b32_e32 v151, 0xffff0000, v42
	v_lshlrev_b32_e32 v92, 16, v29
	v_and_b32_e32 v93, 0xffff0000, v29
	v_lshlrev_b32_e32 v104, 16, v33
	v_and_b32_e32 v105, 0xffff0000, v33
	v_lshlrev_b32_e32 v124, 16, v41
	v_and_b32_e32 v125, 0xffff0000, v41
	v_lshlrev_b32_e32 v128, 16, v28
	v_and_b32_e32 v129, 0xffff0000, v28
	v_lshlrev_b32_e32 v130, 16, v32
	v_and_b32_e32 v131, 0xffff0000, v32
	v_lshlrev_b32_e32 v132, 16, v40
	v_and_b32_e32 v133, 0xffff0000, v40
	v_lshlrev_b32_e32 v134, 16, v44
	v_and_b32_e32 v135, 0xffff0000, v44
	v_lshlrev_b32_e32 v126, 16, v45
	v_and_b32_e32 v127, 0xffff0000, v45
	s_movk_i32 s0, 0x240
	s_waitcnt vmcnt(7)
	v_pk_fma_f32 v[152:153], v[86:87], v[92:93], 0 op_sel_hi:[1,1,0]
	v_pk_fma_f32 v[154:155], v[84:85], v[128:129], 0 op_sel_hi:[1,1,0]
	s_waitcnt vmcnt(6)
	v_pk_fma_f32 v[156:157], v[68:69], v[136:137], 0 op_sel_hi:[1,1,0]
	v_pk_fma_f32 v[158:159], v[66:67], v[144:145], 0 op_sel_hi:[1,1,0]
	s_waitcnt vmcnt(4)
	v_pk_fma_f32 v[156:157], v[72:73], v[138:139], v[156:157]
	v_pk_fma_f32 v[158:159], v[70:71], v[146:147], v[158:159]
	v_pk_fma_f32 v[152:153], v[90:91], v[104:105], v[152:153]
	s_waitcnt vmcnt(2)
	v_pk_fma_f32 v[156:157], v[76:77], v[140:141], v[156:157]
	v_pk_fma_f32 v[158:159], v[74:75], v[148:149], v[158:159]
	s_waitcnt vmcnt(0)
	v_pk_fma_f32 v[142:143], v[80:81], v[142:143], v[156:157]
	v_pk_fma_f32 v[150:151], v[78:79], v[150:151], v[158:159]
	v_mul_f32_e32 v156, 0xbfb8aa3b, v142
	v_mul_f32_e32 v157, 0xbfb8aa3b, v143
	v_exp_f32_e32 v156, v156
	v_exp_f32_e32 v157, v157
	v_mul_f32_e32 v158, 0xbfb8aa3b, v150
	v_mul_f32_e32 v159, 0xbfb8aa3b, v151
	v_add_f32_e32 v156, 1.0, v156
	v_add_f32_e32 v157, 1.0, v157
	v_exp_f32_e32 v158, v158
	v_rcp_f32_e32 v156, v156
	v_rcp_f32_e32 v157, v157
	v_exp_f32_e32 v159, v159
	v_pk_fma_f32 v[154:155], v[88:89], v[130:131], v[154:155]
	v_pk_fma_f32 v[152:153], v[122:123], v[124:125], v[152:153]
	v_pk_mul_f32 v[142:143], v[142:143], v[156:157]
	v_add_f32_e32 v156, 1.0, v158
	v_add_f32_e32 v157, 1.0, v159
	v_lshlrev_b32_e32 v158, 16, v25
	v_and_b32_e32 v159, 0xffff0000, v25
	v_pk_fma_f32 v[86:87], v[86:87], v[158:159], 0 op_sel_hi:[1,1,0]
	v_pk_fma_f32 v[154:155], v[120:121], v[132:133], v[154:155]
	v_pk_fma_f32 v[86:87], v[90:91], v[92:93], v[86:87]
	v_pk_fma_f32 v[134:135], v[100:101], v[134:135], v[154:155]
	v_pk_fma_f32 v[86:87], v[122:123], v[104:105], v[86:87]
	v_mul_f32_e32 v154, 0xbfb8aa3b, v134
	v_pk_fma_f32 v[86:87], v[102:103], v[124:125], v[86:87]
	v_mul_f32_e32 v155, 0xbfb8aa3b, v135
	v_mul_f32_e32 v90, 0xbfb8aa3b, v86
	v_mul_f32_e32 v91, 0xbfb8aa3b, v87
	v_exp_f32_e32 v90, v90
	v_exp_f32_e32 v91, v91
	v_pk_fma_f32 v[126:127], v[102:103], v[126:127], v[152:153]
	v_exp_f32_e32 v154, v154
	v_add_f32_e32 v90, 1.0, v90
	v_add_f32_e32 v91, 1.0, v91
	v_rcp_f32_e32 v90, v90
	v_rcp_f32_e32 v91, v91
	v_exp_f32_e32 v155, v155
	v_mul_f32_e32 v152, 0xbfb8aa3b, v126
	v_mul_f32_e32 v153, 0xbfb8aa3b, v127
	v_pk_mul_f32 v[86:87], v[86:87], v[90:91]
	v_lshlrev_b32_e32 v90, 16, v24
	v_and_b32_e32 v91, 0xffff0000, v24
	v_pk_fma_f32 v[84:85], v[84:85], v[90:91], 0 op_sel_hi:[1,1,0]
	v_exp_f32_e32 v152, v152
	v_pk_fma_f32 v[84:85], v[88:89], v[128:129], v[84:85]
	v_exp_f32_e32 v153, v153
; #define LAS __attribute__((address_space(3)))
; __device__ __forceinline__ unsigned cvt_pk_bf16(float lo, float hi) { const bf16x2_t r = __builtin_convertvector((f32x2){lo, hi}, bf16x2_t); return __builtin_bit_cast(unsigned, r); }
; __device__ __forceinline__ void gdn_prep_item(LAS unsigned char* lds, int item, int b0, PrepRaw& R, int next_item, const bf16_t* qkv, const float* bg, const float* gconv_w, unsigned char* rec, float* gtarr) {
;     ...
;             for (int j = 0; j < 5; ++j) { const u32x4 v = part < 2 ? R.x[part < 2 ? part : 0][j] : xv[j]; const unsigned vv[4] = {v.x, v.y, v.z, v.w}; float x[8];
; #pragma unroll
;                 for (int e = 0; e < 4; ++e) { x[2 * e] = __uint_as_float(vv[e] << 16); x[2 * e + 1] = __uint_as_float(vv[e] & 0xffff0000u); }
;                 if (j < 4) { const f32x4 wa = *(const f32x4*)(gconv_w + j * CONVCH + col), wb = *(const f32x4*)(gconv_w + j * CONVCH + col + 4);
; #pragma unroll
;                     for (int e = 0; e < 8; ++e) y0[e] += (e < 4 ? wa[e] : wb[e - 4]) * x[e]; }
;                 if (j > 0) { const f32x4 wa = *(const f32x4*)(gconv_w + (j - 1) * CONVCH + col), wb = *(const f32x4*)(gconv_w + (j - 1) * CONVCH + col + 4);
; #pragma unroll
;                     for (int e = 0; e < 8; ++e) y1[e] += (e < 4 ? wa[e] : wb[e - 4]) * x[e]; } }
;             float s0 = 0.f, s1 = 0.f;
; #pragma unroll
;             for (int e = 0; e < 8; ++e) { y0[e] = silu_f(y0[e]); y1[e] = silu_f(y1[e]); s0 += y0[e] * y0[e]; s1 += y1[e] * y1[e]; }
;             if (part < 2) {
;                 s0 = row16_sum(s0); s1 = row16_sum(s1);
;                 float sc0 = rsqrtf(s0 + EPS), sc1 = rsqrtf(s1 + EPS); if (part == 0) { sc0 *= 0.08838834764831845f; sc1 *= 0.08838834764831845f; }
; #pragma unroll
;                 for (int e = 0; e < 8; ++e) { y0[e] *= sc0; y1[e] *= sc1; }
;                 LAS unsigned char* img = lds + (part == 0 ? P2_QN : P2_KN);
;                 u32x4 w0, w1; w0.x = cvt_pk_bf16(y0[0], y0[1]); w0.y = cvt_pk_bf16(y0[2], y0[3]); w0.z = cvt_pk_bf16(y0[4], y0[5]); w0.w = cvt_pk_bf16(y0[6], y0[7]);
;                 w1.x = cvt_pk_bf16(y1[0], y1[1]); w1.y = cvt_pk_bf16(y1[2], y1[3]); w1.z = cvt_pk_bf16(y1[4], y1[5]); w1.w = cvt_pk_bf16(y1[6], y1[7]);
;                 *(LAS u32x4*)(img + (i0 * 136 + 8 * cc) * 2) = w0; *(LAS u32x4*)(img + ((i0 + 1) * 136 + 8 * cc) * 2) = w1;
	v_pk_fma_f32 v[84:85], v[120:121], v[130:131], v[84:85]
	v_rcp_f32_e32 v156, v156
	v_pk_fma_f32 v[84:85], v[100:101], v[132:133], v[84:85]
	v_lshlrev_b32_e32 v100, 16, v23
	v_and_b32_e32 v101, 0xffff0000, v23
	v_pk_fma_f32 v[68:69], v[68:69], v[100:101], 0 op_sel_hi:[1,1,0]
	v_mul_f32_e32 v88, 0xbfb8aa3b, v84
	v_pk_fma_f32 v[68:69], v[72:73], v[136:137], v[68:69]
	v_exp_f32_e32 v90, v88
	v_pk_fma_f32 v[68:69], v[76:77], v[138:139], v[68:69]
	v_mul_f32_e32 v88, 0xbfb8aa3b, v85
	v_pk_fma_f32 v[68:69], v[80:81], v[140:141], v[68:69]
	v_lshlrev_b32_e32 v80, 16, v22
	v_and_b32_e32 v81, 0xffff0000, v22
	v_pk_fma_f32 v[66:67], v[66:67], v[80:81], 0 op_sel_hi:[1,1,0]
	v_mul_f32_e32 v72, 0xbfb8aa3b, v68
	v_pk_fma_f32 v[66:67], v[70:71], v[144:145], v[66:67]
	v_exp_f32_e32 v76, v72
	v_pk_fma_f32 v[66:67], v[74:75], v[146:147], v[66:67]
	v_mul_f32_e32 v72, 0xbfb8aa3b, v69
	v_pk_fma_f32 v[66:67], v[78:79], v[148:149], v[66:67]
	v_exp_f32_e32 v77, v72
	v_mul_f32_e32 v70, 0xbfb8aa3b, v66
	v_mul_f32_e32 v71, 0xbfb8aa3b, v67
	v_exp_f32_e32 v70, v70
	v_exp_f32_e32 v71, v71
	v_exp_f32_e32 v91, v88
	v_rcp_f32_e32 v157, v157
	v_add_f32_e32 v70, 1.0, v70
	v_add_f32_e32 v71, 1.0, v71
	v_add_f32_e32 v76, 1.0, v76
	v_add_f32_e32 v77, 1.0, v77
	v_rcp_f32_e32 v70, v70
	v_rcp_f32_e32 v71, v71
	v_rcp_f32_e32 v76, v76
	v_rcp_f32_e32 v77, v77
	v_add_f32_e32 v154, 1.0, v154
	v_add_f32_e32 v155, 1.0, v155
	v_add_f32_e32 v90, 1.0, v90
	v_add_f32_e32 v91, 1.0, v91
	v_rcp_f32_e32 v154, v154
	v_rcp_f32_e32 v155, v155
	v_rcp_f32_e32 v90, v90
	v_rcp_f32_e32 v91, v91
	v_add_f32_e32 v152, 1.0, v152
	v_add_f32_e32 v153, 1.0, v153
	v_pk_mul_f32 v[102:103], v[150:151], v[156:157]
	v_pk_mul_f32 v[66:67], v[66:67], v[70:71]
	v_rcp_f32_e32 v152, v152
	v_rcp_f32_e32 v153, v153
	v_pk_mul_f32 v[104:105], v[102:103], v[102:103]
	v_pk_mul_f32 v[68:69], v[68:69], v[76:77]
	v_pk_mul_f32 v[70:71], v[66:67], v[66:67]
	v_pk_mul_f32 v[92:93], v[142:143], v[142:143]
	v_pk_mul_f32 v[76:77], v[68:69], v[68:69]
	v_mov_b32_e32 v78, v104
	v_mov_b32_e32 v79, v70
	v_mov_b32_e32 v70, v105
	v_pk_mul_f32 v[134:135], v[134:135], v[154:155]
	v_pk_mul_f32 v[72:73], v[84:85], v[90:91]
	v_pk_add_f32 v[70:71], v[78:79], v[70:71]
	v_mov_b32_e32 v78, v92
	v_mov_b32_e32 v79, v76
	v_pk_mul_f32 v[154:155], v[134:135], v[134:135]
	v_pk_mul_f32 v[74:75], v[72:73], v[72:73]
	v_pk_add_f32 v[70:71], v[78:79], v[70:71]
	v_mov_b32_e32 v76, v93
	v_pk_mul_f32 v[126:127], v[126:127], v[152:153]
	v_pk_add_f32 v[70:71], v[76:77], v[70:71]
	v_mov_b32_e32 v76, v154
	v_mov_b32_e32 v77, v74
	v_pk_mul_f32 v[152:153], v[126:127], v[126:127]
	v_pk_mul_f32 v[88:89], v[86:87], v[86:87]
	v_pk_add_f32 v[70:71], v[76:77], v[70:71]
	v_mov_b32_e32 v74, v155
	v_pk_add_f32 v[70:71], v[74:75], v[70:71]
	v_mov_b32_e32 v74, v152
	v_mov_b32_e32 v75, v88
	v_pk_add_f32 v[70:71], v[74:75], v[70:71]
	v_mov_b32_e32 v88, v153
	v_pk_add_f32 v[70:71], v[88:89], v[70:71]
	v_mov_b32_e32 v74, v34
	v_mov_b32_e32 v75, v34
	s_nop 0
	v_mov_b32_dpp v74, v70 quad_perm:[1,0,3,2] row_mask:0xf bank_mask:0xf
	v_mov_b32_dpp v75, v71 quad_perm:[1,0,3,2] row_mask:0xf bank_mask:0xf
	v_pk_add_f32 v[70:71], v[70:71], v[74:75]
	v_mov_b32_e32 v74, v34
	v_mov_b32_e32 v75, v34
	s_nop 0
	v_mov_b32_dpp v74, v70 quad_perm:[2,3,0,1] row_mask:0xf bank_mask:0xf
	v_mov_b32_dpp v75, v71 quad_perm:[2,3,0,1] row_mask:0xf bank_mask:0xf
	v_pk_add_f32 v[70:71], v[70:71], v[74:75]
	v_mov_b32_e32 v74, v34
	v_mov_b32_e32 v75, v34
	s_nop 0
	v_mov_b32_dpp v74, v70 row_ror:4 row_mask:0xf bank_mask:0xf
	v_mov_b32_dpp v75, v71 row_ror:4 row_mask:0xf bank_mask:0xf
	v_pk_add_f32 v[70:71], v[70:71], v[74:75]
	v_mov_b32_e32 v74, v34
	v_mov_b32_e32 v75, v34
	s_nop 0
	v_mov_b32_dpp v74, v70 row_ror:8 row_mask:0xf bank_mask:0xf
	v_mov_b32_dpp v75, v71 row_ror:8 row_mask:0xf bank_mask:0xf
	v_pk_add_f32 v[70:71], v[70:71], v[74:75]
	s_nop 0
	v_pk_add_f32 v[70:71], v[70:71], s[16:17] op_sel_hi:[1,0]
	s_nop 0
	v_mul_f32_e32 v74, 0x4b800000, v70
	v_cmp_gt_f32_e32 vcc, s24, v70
	v_mul_f32_e32 v76, 0x4b800000, v71
	s_nop 0
	v_cndmask_b32_e32 v70, v70, v74, vcc
	v_rsq_f32_e32 v70, v70
	s_nop 0
	v_mul_f32_e32 v74, 0x45800000, v70
	v_cndmask_b32_e32 v70, v70, v74, vcc
	v_cmp_gt_f32_e32 vcc, s24, v71
	v_pk_mul_f32 v[74:75], v[102:103], v[70:71] op_sel_hi:[1,0]
	s_nop 0
	v_cndmask_b32_e32 v71, v71, v76, vcc
	v_rsq_f32_e32 v71, v71
	s_nop 0
	v_pk_mul_f32 v[76:77], v[142:143], v[70:71] op_sel_hi:[1,0]
	v_pk_mul_f32 v[78:79], v[134:135], v[70:71] op_sel_hi:[1,0]
	v_pk_mul_f32 v[80:81], v[126:127], v[70:71] op_sel_hi:[1,0]
	v_mul_f32_e32 v70, 0x45800000, v71
	v_cndmask_b32_e32 v70, v71, v70, vcc
	v_pk_mul_f32 v[84:85], v[66:67], v[70:71] op_sel_hi:[1,0]
	v_pk_mul_f32 v[88:89], v[68:69], v[70:71] op_sel_hi:[1,0]
	v_pk_mul_f32 v[90:91], v[72:73], v[70:71] op_sel_hi:[1,0]
	v_pk_mul_f32 v[86:87], v[86:87], v[70:71] op_sel_hi:[1,0]
	v_cvt_pk_bf16_f32 v66, v84, v85
	v_cvt_pk_bf16_f32 v67, v88, v89
	v_cvt_pk_bf16_f32 v68, v90, v91
	v_cvt_pk_bf16_f32 v69, v86, v87
	v_cvt_pk_bf16_f32 v70, v74, v75
	v_cvt_pk_bf16_f32 v71, v76, v77
	v_cvt_pk_bf16_f32 v72, v78, v79
	v_cvt_pk_bf16_f32 v73, v80, v81
	ds_write_b128 v94, v[66:69] offset:17408
	ds_write_b128 v160, v[70:73] offset:17408
	s_waitcnt lgkmcnt(4)
; #define LAS __attribute__((address_space(3)))
; __device__ __forceinline__ unsigned cvt_pk_bf16(float lo, float hi) { const bf16x2_t r = __builtin_convertvector((f32x2){lo, hi}, bf16x2_t); return __builtin_bit_cast(unsigned, r); }
; __device__ __forceinline__ void gdn_prep_item(LAS unsigned char* lds, int item, int b0, PrepRaw& R, int next_item, const bf16_t* qkv, const float* bg, const float* gconv_w, unsigned char* rec, float* gtarr) {
;     ...
;                 if (part == 1) {
;                     const float f0 = be0 * eg0, f1 = be1 * eg1;
; #pragma unroll
;                     for (int e = 0; e < 8; ++e) *(LAS unsigned*)(lds + P2_KBT + ((8 * cc + e) * 72 + i0) * 2) = cvt_pk_bf16(y0[e] * f0, y1[e] * f1);
;                 }
;             } else {
; #pragma unroll
;                 for (int e = 0; e < 8; ++e) *(LAS unsigned*)(lds + P2_VBT + ((8 * cc + e) * 72 + i0) * 2) = cvt_pk_bf16(y0[e] * be0, y1[e] * be1);
	v_pk_mul_f32 v[66:67], v[36:37], v[96:97]
	v_mov_b32_e32 v68, v84
	v_mov_b32_e32 v69, v74
	v_pk_mul_f32 v[68:69], v[66:67], v[68:69]
	v_mov_b32_e32 v74, v85
	v_cvt_pk_bf16_f32 v70, v68, v69
	v_mad_u32_u24 v68, v114, s0, v95
	v_lshl_add_u32 v84, v68, 1, 0
	v_pk_mul_f32 v[68:69], v[66:67], v[74:75]
	v_add_u32_e32 v71, 0xd000, v84
	v_cvt_pk_bf16_f32 v68, v68, v69
	ds_write2_b32 v71, v70, v68 offset1:36
	v_mov_b32_e32 v68, v88
	v_mov_b32_e32 v69, v76
	v_pk_mul_f32 v[68:69], v[66:67], v[68:69]
	v_mov_b32_e32 v76, v89
	v_cvt_pk_bf16_f32 v70, v68, v69
	v_pk_mul_f32 v[68:69], v[66:67], v[76:77]
	s_nop 0
	v_cvt_pk_bf16_f32 v68, v68, v69
	ds_write2_b32 v71, v70, v68 offset0:72 offset1:108
	v_mov_b32_e32 v68, v90
	v_mov_b32_e32 v69, v78
	v_pk_mul_f32 v[68:69], v[66:67], v[68:69]
	v_mov_b32_e32 v78, v91
	v_cvt_pk_bf16_f32 v70, v68, v69
	v_pk_mul_f32 v[68:69], v[66:67], v[78:79]
	s_nop 0
	v_cvt_pk_bf16_f32 v68, v68, v69
	ds_write2_b32 v71, v70, v68 offset0:144 offset1:180
	v_mov_b32_e32 v68, v86
	v_mov_b32_e32 v69, v80
	v_mov_b32_e32 v80, v87
	v_pk_mul_f32 v[68:69], v[66:67], v[68:69]
	v_pk_mul_f32 v[66:67], v[66:67], v[80:81]
	v_cvt_pk_bf16_f32 v68, v68, v69
	v_cvt_pk_bf16_f32 v66, v66, v67
	ds_write2_b32 v71, v68, v66 offset0:216 offset1:252
	s_movk_i32 s0, 0x5000
	v_add_co_u32_e32 v66, vcc, s0, v98
	s_mov_b32 s0, 0x8000
	s_nop 0
	v_addc_co_u32_e32 v67, vcc, 0, v99, vcc
	v_add_co_u32_e32 v70, vcc, s0, v98
	global_load_dwordx4 v[94:97], v[82:83], off
	s_nop 0
	v_addc_co_u32_e32 v71, vcc, 0, v99, vcc
	s_mov_b32 s0, 0xb000
	global_load_dwordx4 v[66:69], v[66:67], off
	v_add_co_u32_e32 v74, vcc, s0, v98
	global_load_dwordx4 v[70:73], v[70:71], off
	s_nop 0
	v_addc_co_u32_e32 v75, vcc, 0, v99, vcc
	global_load_dwordx4 v[74:77], v[74:75], off
	s_mov_b64 s[0:1], 0x2000
	s_mov_b64 s[4:5], 0x5000
	v_lshlrev_b32_e32 v101, 16, v54
	v_lshlrev_b32_e32 v105, 16, v62
	v_and_b32_e32 v123, 0xffff0000, v54
	v_and_b32_e32 v127, 0xffff0000, v62
	v_lshlrev_b32_e32 v130, 16, v47
	v_lshlrev_b32_e32 v133, 16, v51
	v_lshlrev_b32_e32 v135, 16, v63
	v_and_b32_e32 v54, 0xffff0000, v47
	v_and_b32_e32 v47, 0xffff0000, v51
	v_and_b32_e32 v51, 0xffff0000, v63
	v_lshl_add_u64 v[62:63], v[98:99], 0, s[0:1]
	v_lshl_add_u64 v[78:79], v[98:99], 0, s[4:5]
	global_load_dwordx4 v[90:93], v[62:63], off offset:16
	s_mov_b64 s[6:7], 0x8000
	v_add_u32_e32 v138, 0x8800, v84
	global_load_dwordx4 v[82:85], v[78:79], off offset:16
	s_mov_b64 s[8:9], 0xb000
	v_lshl_add_u64 v[80:81], v[98:99], 0, s[6:7]
	v_lshl_add_u64 v[98:99], v[98:99], 0, s[8:9]
	global_load_dwordx4 v[86:89], v[80:81], off offset:16
	s_nop 0
	global_load_dwordx4 v[78:81], v[98:99], off offset:16
	v_lshlrev_b32_e32 v100, 16, v46
	v_and_b32_e32 v122, 0xffff0000, v46
	v_lshlrev_b32_e32 v103, 16, v50
	v_and_b32_e32 v125, 0xffff0000, v50
	v_lshlrev_b32_e32 v131, 16, v55
	v_mov_b32_e32 v102, v101
	v_mov_b32_e32 v124, v123
	v_mov_b32_e32 v104, v103
	v_mov_b32_e32 v126, v125
	v_mov_b32_e32 v132, v131
	v_lshlrev_b32_e32 v121, 16, v58
	v_and_b32_e32 v129, 0xffff0000, v58
	v_mov_b32_e32 v120, v105
	v_mov_b32_e32 v128, v127
	v_mov_b32_e32 v134, v133
	v_lshlrev_b32_e32 v137, 16, v59
	v_and_b32_e32 v55, 0xffff0000, v55
	v_mov_b32_e32 v136, v135
	v_mov_b32_e32 v46, v55
	v_mov_b32_e32 v50, v47
	s_waitcnt vmcnt(7)
	v_pk_fma_f32 v[62:63], v[94:95], v[100:101], 0 op_sel_hi:[0,1,0]
	v_pk_fma_f32 v[94:95], v[94:95], v[122:123], 0 op_sel:[1,0,0] op_sel_hi:[1,1,0]
	v_pk_fma_f32 v[98:99], v[96:97], v[130:131], 0 op_sel_hi:[0,1,0]
	v_mov_b32_e32 v58, v97
	s_waitcnt vmcnt(6)
	v_pk_fma_f32 v[62:63], v[66:67], v[102:103], v[62:63] op_sel_hi:[0,1,1]
	v_pk_fma_f32 v[66:67], v[66:67], v[124:125], v[94:95] op_sel:[1,0,0]
	v_pk_fma_f32 v[94:95], v[68:69], v[132:133], v[98:99] op_sel_hi:[0,1,1]
	s_waitcnt vmcnt(5)
	v_pk_fma_f32 v[62:63], v[70:71], v[104:105], v[62:63] op_sel_hi:[0,1,1]
	v_pk_fma_f32 v[66:67], v[70:71], v[126:127], v[66:67] op_sel:[1,0,0]
	v_pk_fma_f32 v[70:71], v[72:73], v[134:135], v[94:95] op_sel_hi:[0,1,1]
	s_waitcnt vmcnt(4)
	v_pk_fma_f32 v[62:63], v[74:75], v[120:121], v[62:63] op_sel_hi:[0,1,1]
	v_pk_fma_f32 v[66:67], v[74:75], v[128:129], v[66:67] op_sel:[1,0,0]
	v_pk_fma_f32 v[54:55], v[58:59], v[54:55], 0 op_sel_hi:[0,1,0]
	v_pk_fma_f32 v[70:71], v[76:77], v[136:137], v[70:71] op_sel_hi:[0,1,1]
	v_mul_f32_e32 v58, 0xbfb8aa3b, v63
	v_mul_f32_e32 v68, 0xbfb8aa3b, v62
	v_mul_f32_e32 v72, 0xbfb8aa3b, v67
	v_mul_f32_e32 v74, 0xbfb8aa3b, v66
	v_mul_f32_e32 v75, 0xbfb8aa3b, v71
	v_exp_f32_e32 v58, v58
	v_exp_f32_e32 v68, v68
	v_exp_f32_e32 v72, v72
	v_exp_f32_e32 v74, v74
	v_exp_f32_e32 v75, v75
	v_add_f32_e32 v58, 1.0, v58
	v_add_f32_e32 v68, 1.0, v68
	v_add_f32_e32 v72, 1.0, v72
	v_add_f32_e32 v94, 1.0, v74
	v_add_f32_e32 v96, 1.0, v75
	v_rcp_f32_e32 v75, v58
	v_rcp_f32_e32 v74, v68
	v_rcp_f32_e32 v95, v72
	v_rcp_f32_e32 v94, v94
	v_and_b32_e32 v59, 0xffff0000, v59
	v_pk_mul_f32 v[62:63], v[62:63], v[74:75]
	v_mul_f32_e32 v76, 0xbfb8aa3b, v70
	v_pk_mul_f32 v[66:67], v[66:67], v[94:95]
	v_pk_mul_f32 v[62:63], v[36:37], v[62:63]
	v_pk_mul_f32 v[66:67], v[36:37], v[66:67]
	v_cvt_pk_bf16_f32 v58, v62, v63
	v_cvt_pk_bf16_f32 v62, v66, v67
	ds_write2_b32 v138, v58, v62 offset1:36
	v_mov_b32_e32 v62, v69
	v_pk_fma_f32 v[46:47], v[62:63], v[46:47], v[54:55] op_sel_hi:[0,1,1]
	v_mov_b32_e32 v54, v73
	v_mov_b32_e32 v58, v51
	v_pk_fma_f32 v[46:47], v[54:55], v[50:51], v[46:47] op_sel_hi:[0,1,1]
	v_mov_b32_e32 v50, v77
	v_pk_fma_f32 v[46:47], v[50:51], v[58:59], v[46:47] op_sel_hi:[0,1,1]
	v_mul_f32_e32 v50, 0xbfb8aa3b, v47
	v_exp_f32_e32 v50, v50
	v_mul_f32_e32 v51, 0xbfb8aa3b, v46
	v_exp_f32_e32 v54, v51
	v_exp_f32_e32 v76, v76
	v_add_f32_e32 v50, 1.0, v50
	v_rcp_f32_e32 v51, v50
	v_add_f32_e32 v50, 1.0, v54
	v_rcp_f32_e32 v50, v50
	v_add_f32_e32 v68, 1.0, v76
	v_rcp_f32_e32 v97, v96
	v_rcp_f32_e32 v96, v68
	v_pk_mul_f32 v[46:47], v[46:47], v[50:51]
	v_lshlrev_b32_e32 v51, 16, v52
	v_pk_mul_f32 v[46:47], v[36:37], v[46:47]
	v_pk_mul_f32 v[54:55], v[70:71], v[96:97]
	v_cvt_pk_bf16_f32 v63, v46, v47
	v_lshlrev_b32_e32 v47, 16, v56
	v_lshlrev_b32_e32 v46, 16, v48
	v_pk_mul_f32 v[54:55], v[36:37], v[54:55]
	v_mov_b32_e32 v50, v47
	s_waitcnt vmcnt(3)
; #define LAS __attribute__((address_space(3)))
; __device__ __forceinline__ unsigned cvt_pk_bf16(float lo, float hi) { const bf16x2_t r = __builtin_convertvector((f32x2){lo, hi}, bf16x2_t); return __builtin_bit_cast(unsigned, r); }
; __device__ __forceinline__ void gdn_prep_load(PrepRaw& R, int item, int b0, const bf16_t* qkv, const float* bg, int tid) {
;     const int h = item & 7, c = (item >> 3) % NCHUNK, b = b0 + (item >> 3) / NCHUNK;
;     const int tbase = 64 * c - 48, cc = tid & 15, i0 = (tid >> 4) * 2;
; #pragma unroll
;     for (int part = 0; part < 2; ++part)
; #pragma unroll
;         for (int j = 0; j < 5; ++j) { const int t = tbase + i0 - 3 + j;
;             R.x[part][j] = (t >= 0) ? *(const u32x4*)(qkv + (size_t)(b * LP + t) * CONVCH + part * 1024 + h * 128 + 8 * cc) : (u32x4){0u, 0u, 0u, 0u}; }
; __device__ __forceinline__ void gdn_prep_item(LAS unsigned char* lds, int item, int b0, PrepRaw& R, int next_item, const bf16_t* qkv, const float* bg, const float* gconv_w, unsigned char* rec, float* gtarr) {
;     ...
;             } else {
; #pragma unroll
;                 for (int e = 0; e < 8; ++e) *(LAS unsigned*)(lds + P2_VBT + ((8 * cc + e) * 72 + i0) * 2) = cvt_pk_bf16(y0[e] * be0, y1[e] * be1);
;             }
;             __builtin_amdgcn_sched_barrier(0);
;         }
;     }
;     if (next_item >= 0) gdn_prep_load(R, next_item, b0, qkv, bg, tid);
	v_pk_fma_f32 v[46:47], v[90:91], v[46:47], 0 op_sel_hi:[0,1,0]
	v_cvt_pk_bf16_f32 v62, v54, v55
	v_lshlrev_b32_e32 v55, 16, v64
	v_mov_b32_e32 v54, v51
	s_waitcnt vmcnt(2)
	v_pk_fma_f32 v[46:47], v[82:83], v[50:51], v[46:47] op_sel_hi:[0,1,1]
	v_lshlrev_b32_e32 v59, 16, v60
	v_mov_b32_e32 v58, v55
	s_waitcnt vmcnt(1)
	v_pk_fma_f32 v[46:47], v[86:87], v[54:55], v[46:47] op_sel_hi:[0,1,1]
	s_waitcnt vmcnt(0)
	v_pk_fma_f32 v[46:47], v[78:79], v[58:59], v[46:47] op_sel_hi:[0,1,1]
	v_mul_f32_e32 v50, 0xbfb8aa3b, v47
	v_exp_f32_e32 v50, v50
	v_mul_f32_e32 v51, 0xbfb8aa3b, v46
	v_exp_f32_e32 v54, v51
	v_and_b32_e32 v55, 0xffff0000, v56
	v_add_f32_e32 v50, 1.0, v50
	v_rcp_f32_e32 v51, v50
	v_add_f32_e32 v50, 1.0, v54
	v_and_b32_e32 v54, 0xffff0000, v48
	v_and_b32_e32 v59, 0xffff0000, v52
	v_mov_b32_e32 v58, v55
	v_pk_fma_f32 v[54:55], v[90:91], v[54:55], 0 op_sel:[1,0,0] op_sel_hi:[1,1,0]
	ds_write2_b32 v138, v62, v63 offset0:72 offset1:108
	v_and_b32_e32 v63, 0xffff0000, v64
	v_mov_b32_e32 v62, v59
	v_pk_fma_f32 v[54:55], v[82:83], v[58:59], v[54:55] op_sel:[1,0,0]
	v_and_b32_e32 v67, 0xffff0000, v60
	v_mov_b32_e32 v66, v63
	v_pk_fma_f32 v[54:55], v[86:87], v[62:63], v[54:55] op_sel:[1,0,0]
	v_rcp_f32_e32 v50, v50
	v_pk_fma_f32 v[54:55], v[78:79], v[66:67], v[54:55] op_sel:[1,0,0]
	v_pk_mul_f32 v[46:47], v[46:47], v[50:51]
	v_mul_f32_e32 v48, 0xbfb8aa3b, v55
	v_exp_f32_e32 v48, v48
	v_mul_f32_e32 v52, 0xbfb8aa3b, v54
	v_exp_f32_e32 v52, v52
	v_pk_mul_f32 v[46:47], v[36:37], v[46:47]
	v_add_f32_e32 v48, 1.0, v48
	v_rcp_f32_e32 v59, v48
	v_add_f32_e32 v48, 1.0, v52
	v_rcp_f32_e32 v58, v48
	v_cvt_pk_bf16_f32 v48, v46, v47
	v_lshlrev_b32_e32 v51, 16, v53
	v_pk_mul_f32 v[46:47], v[54:55], v[58:59]
	s_nop 0
	v_pk_mul_f32 v[46:47], v[36:37], v[46:47]
	v_lshlrev_b32_e32 v55, 16, v65
	v_cvt_pk_bf16_f32 v52, v46, v47
	v_lshlrev_b32_e32 v46, 16, v49
	v_lshlrev_b32_e32 v47, 16, v57
	v_mov_b32_e32 v50, v47
	v_pk_fma_f32 v[46:47], v[92:93], v[46:47], 0 op_sel_hi:[0,1,0]
	v_mov_b32_e32 v54, v51
	v_pk_fma_f32 v[46:47], v[84:85], v[50:51], v[46:47] op_sel_hi:[0,1,1]
	v_lshlrev_b32_e32 v59, 16, v61
	v_mov_b32_e32 v58, v55
	v_pk_fma_f32 v[46:47], v[88:89], v[54:55], v[46:47] op_sel_hi:[0,1,1]
	v_pk_fma_f32 v[46:47], v[80:81], v[58:59], v[46:47] op_sel_hi:[0,1,1]
	v_mul_f32_e32 v50, 0xbfb8aa3b, v47
	v_exp_f32_e32 v50, v50
	v_mul_f32_e32 v51, 0xbfb8aa3b, v46
	v_exp_f32_e32 v54, v51
	ds_write2_b32 v138, v48, v52 offset0:144 offset1:180
	v_add_f32_e32 v48, 1.0, v50
	v_rcp_f32_e32 v51, v48
	v_add_f32_e32 v58, 1.0, v54
	v_and_b32_e32 v55, 0xffff0000, v57
	v_and_b32_e32 v54, 0xffff0000, v49
	v_mov_b32_e32 v50, v93
	v_and_b32_e32 v49, 0xffff0000, v53
	v_mov_b32_e32 v48, v55
	v_pk_fma_f32 v[54:55], v[50:51], v[54:55], 0 op_sel_hi:[0,1,0]
	v_mov_b32_e32 v50, v85
	v_and_b32_e32 v53, 0xffff0000, v65
	v_mov_b32_e32 v52, v49
	v_pk_fma_f32 v[48:49], v[50:51], v[48:49], v[54:55] op_sel_hi:[0,1,1]
	v_mov_b32_e32 v50, v89
	v_and_b32_e32 v57, 0xffff0000, v61
	v_mov_b32_e32 v56, v53
	v_pk_fma_f32 v[48:49], v[50:51], v[52:53], v[48:49] op_sel_hi:[0,1,1]
	v_mov_b32_e32 v50, v81
	v_pk_fma_f32 v[48:49], v[50:51], v[56:57], v[48:49] op_sel_hi:[0,1,1]
	v_mul_f32_e32 v50, 0xbfb8aa3b, v49
	v_exp_f32_e32 v52, v50
	v_mul_f32_e32 v50, 0xbfb8aa3b, v48
	v_exp_f32_e32 v54, v50
	v_rcp_f32_e32 v50, v58
	v_add_f32_e32 v52, 1.0, v52
	v_rcp_f32_e32 v53, v52
	v_add_f32_e32 v52, 1.0, v54
	v_rcp_f32_e32 v52, v52
	v_pk_mul_f32 v[46:47], v[46:47], v[50:51]
	s_nop 0
	v_pk_mul_f32 v[46:47], v[36:37], v[46:47]
	s_nop 0
	v_cvt_pk_bf16_f32 v50, v46, v47
	v_pk_mul_f32 v[46:47], v[48:49], v[52:53]
	s_nop 0
	v_pk_mul_f32 v[36:37], v[36:37], v[46:47]
	s_nop 0
	v_cvt_pk_bf16_f32 v36, v36, v37
	ds_write2_b32 v138, v50, v36 offset0:216 offset1:252
	s_cmp_gt_i32 s14, -1
	v_lshlrev_b32_e32 v54, 4, v116
	s_cbranch_scc0 .LBB0_508
	s_lshr_b32 s0, s14, 3
	s_mul_hi_u32 s1, s0, 0x1f07c1f1
	s_lshr_b32 s1, s1, 2
	s_mul_i32 s1, s1, 33
	s_and_b32 s34, s14, 7
	s_sub_i32 s0, s0, s1
	s_mul_hi_u32 s1, s14, 0x3e0f83e1
	s_lshr_b32 s14, s1, 6
	s_lshl_b32 s35, s0, 6
	s_lshl_b32 s0, s34, 8
	s_add_u32 s0, s88, s0
	s_addc_u32 s1, s89, 0
	v_and_b32_e32 v2, 0xf0, v54
	v_mov_b32_e32 v3, v34
	v_mov_b32_e32 v4, v34
	v_mov_b32_e32 v5, v34
	v_add_u32_e32 v18, s35, v119
	s_mulk_i32 s14, 0x810
	v_lshl_add_u64 v[46:47], s[0:1], 0, v[2:3]
	v_mov_b32_e32 v2, v34
	v_mov_b64_e32 v[8:9], v[4:5]
	v_cmp_lt_i32_e32 vcc, -1, v18
	v_add_u32_e32 v26, s14, v18
	v_mov_b64_e32 v[6:7], v[2:3]
	s_and_saveexec_b64 s[0:1], vcc
	s_cbranch_execz .LBB0_485
	v_mad_u64_u32 v[6:7], s[4:5], v26, s2, v[46:47]
	global_load_dwordx4 v[6:9], v[6:7], off

; __device__ __forceinline__ int fresh_tid() { int t = threadIdx.x; asm volatile("" : "+v"(t)); return t; }
; __device__ __forceinline__ void gdn_prep_load(PrepRaw& R, int item, int b0, const bf16_t* qkv, const float* bg, int tid) {
;     const int h = item & 7, c = (item >> 3) % NCHUNK, b = b0 + (item >> 3) / NCHUNK;
;     const int tbase = 64 * c - 48, cc = tid & 15, i0 = (tid >> 4) * 2;
; #pragma unroll
;     for (int part = 0; part < 2; ++part)
; #pragma unroll
;         for (int j = 0; j < 5; ++j) { const int t = tbase + i0 - 3 + j;
;             R.x[part][j] = (t >= 0) ? *(const u32x4*)(qkv + (size_t)(b * LP + t) * CONVCH + part * 1024 + h * 128 + 8 * cc) : (u32x4){0u, 0u, 0u, 0u}; }
; __device__ __forceinline__ void gdn_all(LAS unsigned char* lds, const XcdBarrier& xbar, const int G, const int bx, unsigned char* ws, float* out, const bf16_t* qkv, const float* bg, const float* gconv_w, ...
;     ...
;     if (nlate > 0 && bx >= G - nlate) {
;         const int item = nfull * G + (bx - (G - nlate)); PrepRaw R; gdn_prep_load(R, item, 0, qkv, bg, fresh_tid());
;         gdn_prep_item(lds, item, 0, R, -1, qkv, bg, gconv_w, gdn_rec(ws, out, item), gtarr);
.LBB0_612:
	s_or_b64 exec, exec, s[0:1]
	s_mul_i32 s3, s3, s96
	v_readlane_b32 s16, v245, 19
	s_sub_i32 s2, 0x840, s3
	v_readlane_b32 s30, v245, 33
	v_readlane_b32 s31, v245, 34
	s_add_u32 s14, s30, 0x9000
	s_addc_u32 s15, s31, 0
	v_readlane_b32 s17, v245, 20
	s_cmpk_lt_i32 s3, 0x840
	s_cselect_b64 s[16:17], -1, 0
	s_and_b64 vcc, exec, s[16:17]
	v_readlane_b32 s18, v245, 21
	v_readlane_b32 s19, v245, 22
	v_readlane_b32 s20, v245, 23
	v_readlane_b32 s21, v245, 24
	v_readlane_b32 s22, v245, 25
	v_readlane_b32 s23, v245, 26
	v_readlane_b32 s24, v245, 27
	v_readlane_b32 s25, v245, 28
	v_readlane_b32 s26, v245, 29
	v_readlane_b32 s27, v245, 30
	v_readlane_b32 s28, v245, 31
	v_readlane_b32 s29, v245, 32
	s_waitcnt lgkmcnt(0)
	s_barrier
	s_cbranch_vccz .LBB0_704
	s_cmp_lt_u32 s94, 64
	s_cbranch_scc1 .LBB0_704
	s_mov_b32 s99, 0
.Llt_loop:
	s_mul_i32 s18, s99, 0xc0
	s_add_i32 s18, s18, s94
	s_addk_i32 s18, 0x6c0
	s_cmpk_ge_u32 s18, 0x840
	s_cbranch_scc1 .LBB0_704
	s_and_b32 s100, s18, 7
	s_lshr_b32 s101, s18, 3
	s_and_b32 s98, s101, 7
	s_lshr_b32 s101, s101, 3
	s_mul_i32 s98, s98, 33
	s_add_i32 s98, s98, s101
	s_lshl_b32 s98, s98, 3
	s_or_b32 s18, s98, s100
	s_ashr_i32 s0, s18, 3
	s_mul_hi_i32 s1, s0, 0x3e0f83e1
	s_lshr_b32 s4, s1, 31
	s_ashr_i32 s1, s1, 3
	s_add_i32 s19, s1, s4
	s_mul_i32 s1, s19, 33
	v_mov_b32_e32 v1, v0
	s_sub_i32 s0, s0, s1
	s_and_b32 s23, s18, 7
	s_lshl_b32 s24, s0, 6
	s_waitcnt vmcnt(0)
	v_ashrrev_i32_e32 v2, 3, v1
	v_and_b32_e32 v2, -2, v2
	s_sub_i32 s22, s24, 51
	s_lshl_b32 s0, s23, 8
	v_add_u32_e32 v8, s22, v2
	s_add_u32 s0, s88, s0
	v_lshlrev_b32_e32 v2, 4, v1
	s_mulk_i32 s19, 0x810
	s_addc_u32 s1, s89, 0
	v_and_b32_e32 v90, 0xf0, v2
	v_mov_b32_e32 v91, 0
	v_lshl_add_u64 v[2:3], s[0:1], 0, v[90:91]
	v_cmp_lt_i32_e32 vcc, -1, v8
	v_add_u32_e32 v4, s19, v8
	v_mov_b32_e32 v42, 0
	v_mov_b32_e32 v43, 0
	v_mov_b32_e32 v44, 0
	v_mov_b32_e32 v45, 0
	s_and_saveexec_b64 s[0:1], vcc
	s_cbranch_execz .LBB0_616
	s_movk_i32 s4, 0x1800
	v_mad_i64_i32 v[6:7], s[4:5], v4, s4, v[2:3]
	global_load_dwordx4 v[42:45], v[6:7], off

; __device__ __forceinline__ void gdn_prep_item(LAS unsigned char* lds, int item, int b0, PrepRaw& R, int next_item, const bf16_t* qkv, const float* bg, const float* gconv_w, unsigned char* rec, float* gtarr) {
;     ...
;     if (wave == 0) {
;         float G = R.gi;
; #pragma unroll
;         for (int o = 1; o < 64; o <<= 1) { const float v = __shfl_up(G, o); if (lane >= o) G += v; }
;         const float Gl = __shfl(G, 63);
;         Gs[lane] = G; Bs[lane] = R.be; EG[lane] = __expf(G); DKs[lane] = __expf(Gl - G);
;         if (lane == 0) gtarr[item] = __expf(Gl);
;     }
.LBB0_648:
	s_or_b64 exec, exec, s[0:1]
	s_ashr_i32 s19, s18, 31
	s_cmp_lg_u32 s20, 0
	v_and_b32_e32 v101, 63, v99
	s_cbranch_scc1 .LBB0_652
	v_mbcnt_hi_u32_b32 v62, -1, v220
	v_and_b32_e32 v63, 64, v62
	v_add_u32_e32 v65, -1, v62
	v_cmp_lt_i32_e32 vcc, v65, v63
	v_add_u32_e32 v66, -2, v62
	v_cmp_lt_i32_e64 s[0:1], v66, v63
	v_cndmask_b32_e32 v65, v65, v62, vcc
	v_lshlrev_b32_e32 v65, 2, v65
	s_waitcnt vmcnt(1)
	ds_bpermute_b32 v65, v65, v64
	v_cmp_eq_u32_e32 vcc, 0, v101
	s_waitcnt lgkmcnt(0)
	v_add_f32_e32 v65, v64, v65
	v_cndmask_b32_e32 v64, v65, v64, vcc
	v_cndmask_b32_e64 v65, v66, v62, s[0:1]
	v_lshlrev_b32_e32 v65, 2, v65
	ds_bpermute_b32 v65, v65, v64
	v_cmp_gt_u32_e64 s[0:1], 2, v101
	s_waitcnt lgkmcnt(0)
	v_add_f32_e32 v65, v64, v65
	v_cndmask_b32_e64 v64, v65, v64, s[0:1]
	v_add_u32_e32 v65, -4, v62
	v_cmp_lt_i32_e64 s[0:1], v65, v63
	s_nop 1
	v_cndmask_b32_e64 v65, v65, v62, s[0:1]
	v_lshlrev_b32_e32 v65, 2, v65
	ds_bpermute_b32 v65, v65, v64
	v_cmp_gt_u32_e64 s[0:1], 4, v101
	s_waitcnt lgkmcnt(0)
	v_add_f32_e32 v65, v64, v65
	v_cndmask_b32_e64 v64, v65, v64, s[0:1]
	v_add_u32_e32 v65, -8, v62
	v_cmp_lt_i32_e64 s[0:1], v65, v63
	s_nop 1
	v_cndmask_b32_e64 v65, v65, v62, s[0:1]
	v_lshlrev_b32_e32 v65, 2, v65
	ds_bpermute_b32 v65, v65, v64
	v_cmp_gt_u32_e64 s[0:1], 8, v101
	s_waitcnt lgkmcnt(0)
	v_add_f32_e32 v65, v64, v65
	v_cndmask_b32_e64 v64, v65, v64, s[0:1]
	v_add_u32_e32 v65, -16, v62
	v_cmp_lt_i32_e64 s[0:1], v65, v63
	s_nop 1
	v_cndmask_b32_e64 v65, v65, v62, s[0:1]
	v_lshlrev_b32_e32 v65, 2, v65
	ds_bpermute_b32 v65, v65, v64
	v_cmp_gt_u32_e64 s[0:1], 16, v101
	s_waitcnt lgkmcnt(0)
	v_add_f32_e32 v65, v64, v65
	v_cndmask_b32_e64 v64, v65, v64, s[0:1]
	v_subrev_u32_e32 v65, 32, v62
	v_cmp_lt_i32_e64 s[0:1], v65, v63
	s_nop 1
	v_cndmask_b32_e64 v63, v65, v62, s[0:1]
	v_lshlrev_b32_e32 v63, 2, v63
	ds_bpermute_b32 v63, v63, v64
	v_cmp_gt_u32_e64 s[0:1], 32, v101
	s_waitcnt lgkmcnt(0)
	v_add_f32_e32 v63, v64, v63
	v_cndmask_b32_e64 v63, v63, v64, s[0:1]
	v_bfrev_b32_e32 v64, 0.5
	v_lshl_or_b32 v62, v62, 2, v64
	ds_bpermute_b32 v62, v62, v63
	v_lshl_add_u32 v64, v101, 2, 0
	v_add_u32_e32 v65, 0x1d000, v64
	ds_write_b32 v65, v63
	v_add_u32_e32 v65, 0x1d100, v64
	s_waitcnt vmcnt(0)
	ds_write_b32 v65, v58
	v_mul_f32_e32 v58, 0x3fb8aa3b, v63
	s_waitcnt lgkmcnt(2)
	v_sub_f32_e32 v63, v62, v63
	v_exp_f32_e32 v58, v58
	v_mul_f32_e32 v63, 0x3fb8aa3b, v63
	v_exp_f32_e32 v63, v63
	v_add_u32_e32 v65, 0x1d200, v64
	ds_write_b32 v65, v58
	v_add_u32_e32 v58, 0x1d300, v64
	ds_write_b32 v58, v63
	s_and_saveexec_b64 s[0:1], vcc
	s_cbranch_execz .LBB0_651
	v_mul_f32_e32 v58, 0x3fb8aa3b, v62
	v_exp_f32_e32 v58, v58
	s_lshl_b64 s[4:5], s[18:19], 2
	s_add_u32 s4, s58, s4
	s_addc_u32 s5, s57, s5
	v_mov_b32_e32 v62, 0
	global_store_dword v62, v58, s[4:5] sc0 sc1

; #define LAS __attribute__((address_space(3)))
; __device__ __forceinline__ void gdn_prep_item(LAS unsigned char* lds, int item, int b0, PrepRaw& R, int next_item, const bf16_t* qkv, const float* bg, const float* gconv_w, unsigned char* rec, float* gtarr) {
;     ...
;             const int i = 16 * rt + l15; const float Gi = Gs[i];
; #pragma unroll
;             for (int r = 0; r < 4; ++r) { const int ia = 32 * s + 4 * g + r, ib = ia + 16;
;                 a0[r] = (i >= ia) ? a0[r] * __expf(Gi - Gs[ia]) : 0.f; a1[r] = (i >= ib) ? a1[r] * __expf(Gi - Gs[ib]) : 0.f; }
;             *(bf16x8*)(rec + REC_AM + ((rt * 2 + s) * 64 + lane) * 16) = pack8(a0, a1);
;         }
;     }
;     __syncthreads();
;     if (tid < 64) { const int blk = tid >> 4, cidx = tid & 15; float x[16];
; #pragma unroll
;         for (int i = 0; i < 16; ++i) x[i] = (i == cidx) ? 1.f : 0.f;
; #pragma unroll
;         for (int i = 1; i < 16; ++i) { float a = 0.f; const LAS float* row = Lf + (16 * blk + i) * LS + 16 * blk;
; #pragma unroll
;             for (int j4 = 0; j4 < (i + 3) / 4; ++j4) { const f32x4 l4 = *(const LAS f32x4*)(row + 4 * j4);
; #pragma unroll
;                 for (int e = 0; e < 4; ++e) if (4 * j4 + e < i) a += l4[e] * x[4 * j4 + e]; }
;             if (i > cidx) x[i] = -a; }
; #pragma unroll
;         for (int i = 0; i < 16; ++i) Tf[(16 * blk + i) * LS + 16 * blk + cidx] = x[i];
;     }
.LBB0_687:
	s_or_b64 exec, exec, s[0:1]
	s_add_i32 s0, s18, 0xfffff9c8
	s_cmpk_lt_i32 s18, 0x638
	s_cselect_b32 s0, s18, s0
	s_cselect_b32 s1, s19, 0
	v_readlane_b32 s36, v245, 19
	v_readlane_b32 s48, v245, 31
	v_readlane_b32 s49, v245, 32
	s_mul_i32 s1, s1, 0x12000
	s_mul_hi_u32 s6, s0, 0x12000
	s_cselect_b32 s5, s64, s49
	s_cselect_b32 s4, s33, s48
	s_add_i32 s6, s6, s1
	s_mul_i32 s0, s0, 0x12000
	v_cvt_pk_bf16_f32 v12, v13, v12
	v_cvt_pk_bf16_f32 v13, v7, v8
	v_lshlrev_b32_e32 v7, 4, v101
	s_add_u32 s4, s4, s0
	s_waitcnt lgkmcnt(0)
	v_cvt_pk_bf16_f32 v14, v6, v2
	v_lshl_or_b32 v2, s20, 10, v7
	s_addc_u32 s5, s5, s6
	v_cvt_pk_bf16_f32 v15, v3, v4
	v_ashrrev_i32_e32 v3, 31, v2
	v_lshl_add_u64 v[2:3], s[4:5], 0, v[2:3]
	v_add_co_u32_e32 v2, vcc, 0xc000, v2
	v_readlane_b32 s37, v245, 20
	s_nop 0
	v_addc_co_u32_e32 v3, vcc, 0, v3, vcc
	v_cmp_gt_i32_e32 vcc, 64, v99
	v_readlane_b32 s38, v245, 21
	v_readlane_b32 s39, v245, 22
	v_readlane_b32 s40, v245, 23
	v_readlane_b32 s41, v245, 24
	v_readlane_b32 s42, v245, 25
	v_readlane_b32 s43, v245, 26
	v_readlane_b32 s44, v245, 27
	v_readlane_b32 s45, v245, 28
	v_readlane_b32 s46, v245, 29
	v_readlane_b32 s47, v245, 30
	v_readlane_b32 s50, v245, 33
	v_readlane_b32 s51, v245, 34
	global_store_dwordx4 v[2:3], v[12:15], off sc0 sc1
	s_barrier
	s_and_saveexec_b64 s[6:7], vcc
	s_cbranch_execz .LBB0_689
	v_and_b32_e32 v2, -16, v99
	v_lshlrev_b32_e32 v26, 2, v2
	v_add_u32_e32 v27, s8, v26
	s_movk_i32 s8, 0x110
	v_mul_lo_u32 v28, v2, s8
	v_add_u32_e32 v29, v27, v28
	ds_read_b128 v[2:5], v29 offset:272
	ds_read_b128 v[12:15], v29 offset:544
	v_cmp_eq_u32_e32 vcc, 0, v1
	v_cmp_eq_u32_e64 s[0:1], 1, v1
	s_nop 0
	v_cndmask_b32_e64 v6, 0, 1.0, vcc
	v_cndmask_b32_e64 v8, 0, 1.0, s[0:1]
	s_waitcnt lgkmcnt(1)
	v_fma_f32 v2, v6, v2, 0
	v_cndmask_b32_e64 v8, v8, -v2, vcc
	ds_read_b128 v[2:5], v29 offset:816
	v_cmp_eq_u32_e64 s[0:1], 2, v1
	s_waitcnt lgkmcnt(1)
	v_fma_f32 v12, v6, v12, 0
	v_fmac_f32_e32 v12, v13, v8
	v_cndmask_b32_e64 v9, 0, 1.0, s[0:1]
	v_cmp_gt_u32_e32 vcc, 2, v1
	v_cmp_eq_u32_e64 s[0:1], 3, v1
	s_nop 0
	v_cndmask_b32_e64 v9, v9, -v12, vcc
	ds_read_b128 v[12:15], v29 offset:1088
	s_waitcnt lgkmcnt(1)
	v_fma_f32 v2, v6, v2, 0
	v_fmac_f32_e32 v2, v3, v8
	v_cndmask_b32_e64 v16, 0, 1.0, s[0:1]
	v_fmac_f32_e32 v2, v4, v9
	v_cmp_gt_u32_e32 vcc, 3, v1
	s_waitcnt lgkmcnt(0)
	v_fma_f32 v12, v6, v12, 0
	v_fmac_f32_e32 v12, v13, v8
	v_cndmask_b32_e64 v32, v16, -v2, vcc
	ds_read_b128 v[2:5], v29 offset:1360
	v_cmp_eq_u32_e64 s[0:1], 4, v1
	v_fmac_f32_e32 v12, v14, v9
	v_fmac_f32_e32 v12, v15, v32
	v_cndmask_b32_e64 v17, 0, 1.0, s[0:1]
	v_cmp_gt_u32_e32 vcc, 4, v1
	v_cmp_eq_u32_e64 s[0:1], 5, v1
	s_nop 0
	v_cndmask_b32_e64 v33, v17, -v12, vcc
	ds_read_b128 v[12:15], v29 offset:1376
	s_waitcnt lgkmcnt(0)
	v_fma_f32 v13, v6, v2, 0
	v_fmac_f32_e32 v13, v8, v3
	v_fmac_f32_e32 v13, v4, v9
	v_fmac_f32_e32 v13, v5, v32
	ds_read_b128 v[2:5], v29 offset:1632
	v_cndmask_b32_e64 v18, 0, 1.0, s[0:1]
	v_fmac_f32_e32 v13, v12, v33
	v_cmp_gt_u32_e32 vcc, 5, v1
	v_cmp_eq_u32_e64 s[0:1], 6, v1
	s_nop 0
	v_cndmask_b32_e64 v34, v18, -v13, vcc
	ds_read_b128 v[12:15], v29 offset:1648
	s_waitcnt lgkmcnt(0)
	v_fma_f32 v14, v6, v2, 0
	v_fmac_f32_e32 v14, v8, v3
	v_fmac_f32_e32 v14, v4, v9
	v_fmac_f32_e32 v14, v5, v32
	ds_read_b128 v[2:5], v29 offset:1904
	v_fmac_f32_e32 v14, v12, v33
	v_cndmask_b32_e64 v19, 0, 1.0, s[0:1]
	v_fmac_f32_e32 v14, v13, v34
	v_cmp_gt_u32_e32 vcc, 6, v1
	v_cmp_eq_u32_e64 s[0:1], 7, v1
	s_nop 0
	v_cndmask_b32_e64 v35, v19, -v14, vcc
	ds_read_b128 v[12:15], v29 offset:1920
	s_waitcnt lgkmcnt(0)
	v_fma_f32 v15, v6, v2, 0
	v_fmac_f32_e32 v15, v8, v3
	v_fmac_f32_e32 v15, v9, v4
	v_fmac_f32_e32 v15, v5, v32
	ds_read_b128 v[2:5], v29 offset:2176
	v_fmac_f32_e32 v15, v12, v33
	v_fmac_f32_e32 v15, v13, v34
	v_cndmask_b32_e64 v20, 0, 1.0, s[0:1]
	v_fmac_f32_e32 v15, v14, v35
	v_cmp_gt_u32_e32 vcc, 7, v1
	v_cmp_eq_u32_e64 s[0:1], 8, v1
	s_nop 0
	v_cndmask_b32_e64 v36, v20, -v15, vcc
	ds_read_b128 v[12:15], v29 offset:2192
	s_waitcnt lgkmcnt(1)
	v_fma_f32 v16, v6, v2, 0
	v_fmac_f32_e32 v16, v8, v3
	v_fmac_f32_e32 v16, v9, v4
	v_fmac_f32_e32 v16, v32, v5
	ds_read_b128 v[2:5], v29 offset:2448
	s_waitcnt lgkmcnt(1)
	v_fmac_f32_e32 v16, v12, v33
	v_fmac_f32_e32 v16, v13, v34
	v_fmac_f32_e32 v16, v14, v35
	v_fmac_f32_e32 v16, v15, v36
	ds_read_b128 v[12:15], v29 offset:2464
	s_waitcnt lgkmcnt(1)
	v_fma_f32 v20, v6, v2, 0
	v_fmac_f32_e32 v20, v8, v3
	v_fmac_f32_e32 v20, v9, v4
	v_cndmask_b32_e64 v21, 0, 1.0, s[0:1]
	v_cmp_gt_u32_e32 vcc, 8, v1
	v_fmac_f32_e32 v20, v32, v5
	ds_read_b128 v[2:5], v29 offset:2480
	v_cndmask_b32_e64 v37, v21, -v16, vcc
	s_waitcnt lgkmcnt(1)
	v_fmac_f32_e32 v20, v33, v12
	ds_read_b128 v[16:19], v29 offset:2720
	v_fmac_f32_e32 v20, v13, v34
	v_fmac_f32_e32 v20, v14, v35
	v_fmac_f32_e32 v20, v15, v36
	s_waitcnt lgkmcnt(1)
	v_fmac_f32_e32 v20, v2, v37
	ds_read_b128 v[2:5], v29 offset:2736
	ds_read_b128 v[12:15], v29 offset:2752
	s_waitcnt lgkmcnt(2)
; #define LAS __attribute__((address_space(3)))
; __device__ __forceinline__ void gdn_prep_item(LAS unsigned char* lds, int item, int b0, PrepRaw& R, int next_item, const bf16_t* qkv, const float* bg, const float* gconv_w, unsigned char* rec, float* gtarr) {
;     ...
;     if (tid < 64) { const int blk = tid >> 4, cidx = tid & 15; float x[16];
; #pragma unroll
;         for (int i = 0; i < 16; ++i) x[i] = (i == cidx) ? 1.f : 0.f;
; #pragma unroll
;         for (int i = 1; i < 16; ++i) { float a = 0.f; const LAS float* row = Lf + (16 * blk + i) * LS + 16 * blk;
; #pragma unroll
;             for (int j4 = 0; j4 < (i + 3) / 4; ++j4) { const f32x4 l4 = *(const LAS f32x4*)(row + 4 * j4);
; #pragma unroll
;                 for (int e = 0; e < 4; ++e) if (4 * j4 + e < i) a += l4[e] * x[4 * j4 + e]; }
;             if (i > cidx) x[i] = -a; }
; #pragma unroll
;         for (int i = 0; i < 16; ++i) Tf[(16 * blk + i) * LS + 16 * blk + cidx] = x[i];
	v_fma_f32 v16, v6, v16, 0
	v_fmac_f32_e32 v16, v8, v17
	v_fmac_f32_e32 v16, v9, v18
	v_fmac_f32_e32 v16, v32, v19
	s_waitcnt lgkmcnt(1)
	v_fmac_f32_e32 v16, v33, v2
	v_fmac_f32_e32 v16, v34, v3
	v_fmac_f32_e32 v16, v4, v35
	v_fmac_f32_e32 v16, v5, v36
	ds_read_b128 v[2:5], v29 offset:2992
	v_cmp_eq_u32_e64 s[0:1], 9, v1
	v_cmp_gt_u32_e32 vcc, 9, v1
	s_waitcnt lgkmcnt(1)
	v_fmac_f32_e32 v16, v12, v37
	v_cndmask_b32_e64 v22, 0, 1.0, s[0:1]
	v_cmp_eq_u32_e64 s[0:1], 10, v1
	v_cndmask_b32_e64 v38, v22, -v20, vcc
	v_fmac_f32_e32 v16, v13, v38
	v_cndmask_b32_e64 v23, 0, 1.0, s[0:1]
	v_cmp_gt_u32_e32 vcc, 10, v1
	ds_read_b128 v[12:15], v29 offset:3008
	v_cmp_eq_u32_e64 s[0:1], 11, v1
	v_cndmask_b32_e64 v39, v23, -v16, vcc
	s_waitcnt lgkmcnt(1)
	v_fma_f32 v16, v6, v2, 0
	v_fmac_f32_e32 v16, v8, v3
	v_fmac_f32_e32 v16, v9, v4
	v_fmac_f32_e32 v16, v32, v5
	s_waitcnt lgkmcnt(0)
	v_fmac_f32_e32 v16, v33, v12
	ds_read_b128 v[2:5], v29 offset:3024
	v_fmac_f32_e32 v16, v34, v13
	v_fmac_f32_e32 v16, v35, v14
	v_fmac_f32_e32 v16, v15, v36
	ds_read_b128 v[12:15], v29 offset:3264
	s_waitcnt lgkmcnt(1)
	v_fmac_f32_e32 v16, v2, v37
	v_fmac_f32_e32 v16, v3, v38
	v_cndmask_b32_e64 v24, 0, 1.0, s[0:1]
	v_fmac_f32_e32 v16, v4, v39
	v_cmp_gt_u32_e32 vcc, 11, v1
	ds_read_b128 v[2:5], v29 offset:3280
	v_cmp_eq_u32_e64 s[0:1], 12, v1
	v_cndmask_b32_e64 v24, v24, -v16, vcc
	s_waitcnt lgkmcnt(1)
	v_fma_f32 v16, v6, v12, 0
	v_fmac_f32_e32 v16, v8, v13
	v_fmac_f32_e32 v16, v9, v14
	v_fmac_f32_e32 v16, v32, v15
	ds_read_b128 v[12:15], v29 offset:3296
	s_waitcnt lgkmcnt(1)
	v_fmac_f32_e32 v16, v33, v2
	v_fmac_f32_e32 v16, v34, v3
	v_fmac_f32_e32 v16, v35, v4
	v_fmac_f32_e32 v16, v36, v5
	ds_read_b128 v[2:5], v29 offset:3536
	s_waitcnt lgkmcnt(1)
	v_fmac_f32_e32 v16, v12, v37
	v_fmac_f32_e32 v16, v13, v38
	v_fmac_f32_e32 v16, v14, v39
	v_cndmask_b32_e64 v25, 0, 1.0, s[0:1]
	v_fmac_f32_e32 v16, v15, v24
	v_cmp_gt_u32_e32 vcc, 12, v1
	ds_read_b128 v[12:15], v29 offset:3552
	v_cmp_eq_u32_e64 s[0:1], 13, v1
	v_cndmask_b32_e64 v25, v25, -v16, vcc
	s_waitcnt lgkmcnt(1)
	v_fma_f32 v16, v6, v2, 0
	v_fmac_f32_e32 v16, v8, v3
	v_fmac_f32_e32 v16, v9, v4
	v_fmac_f32_e32 v16, v32, v5
	ds_read_b128 v[2:5], v29 offset:3568
	s_waitcnt lgkmcnt(1)
	v_fmac_f32_e32 v16, v33, v12
	v_fmac_f32_e32 v16, v34, v13
	v_fmac_f32_e32 v16, v35, v14
	v_fmac_f32_e32 v16, v36, v15
	ds_read_b128 v[12:15], v29 offset:3584
	s_waitcnt lgkmcnt(1)
	v_fmac_f32_e32 v16, v37, v2
	v_fmac_f32_e32 v16, v3, v38
	v_fmac_f32_e32 v16, v4, v39
	v_fmac_f32_e32 v16, v5, v24
	ds_read_b128 v[2:5], v29 offset:3808
	v_cndmask_b32_e64 v30, 0, 1.0, s[0:1]
	s_waitcnt lgkmcnt(1)
	v_fmac_f32_e32 v16, v12, v25
	v_cmp_gt_u32_e32 vcc, 13, v1
	ds_read_b128 v[12:15], v29 offset:3824
	v_cmp_eq_u32_e64 s[0:1], 14, v1
	v_cndmask_b32_e64 v30, v30, -v16, vcc
	s_waitcnt lgkmcnt(1)
	v_fma_f32 v16, v6, v2, 0
	v_fmac_f32_e32 v16, v8, v3
	v_fmac_f32_e32 v16, v9, v4
	v_fmac_f32_e32 v16, v32, v5
	ds_read_b128 v[2:5], v29 offset:3840
	s_waitcnt lgkmcnt(1)
	v_fmac_f32_e32 v16, v33, v12
	v_fmac_f32_e32 v16, v34, v13
	v_fmac_f32_e32 v16, v35, v14
	v_fmac_f32_e32 v16, v36, v15
	ds_read_b128 v[12:15], v29 offset:3856
	s_waitcnt lgkmcnt(1)
	v_fmac_f32_e32 v16, v37, v2
	v_or_b32_e32 v2, 15, v99
	v_fmac_f32_e32 v16, v38, v3
	v_mul_lo_u32 v29, v2, s8
	v_fmac_f32_e32 v16, v4, v39
	v_add_u32_e32 v20, v27, v29
	v_fmac_f32_e32 v16, v5, v24
	ds_read_b128 v[2:5], v20
	s_waitcnt lgkmcnt(1)
	v_fmac_f32_e32 v16, v12, v25
	v_cndmask_b32_e64 v31, 0, 1.0, s[0:1]
	v_fmac_f32_e32 v16, v13, v30
	v_cmp_gt_u32_e32 vcc, 14, v1
	s_waitcnt lgkmcnt(0)
	v_fma_f32 v2, v6, v2, 0
	v_fmac_f32_e32 v2, v8, v3
	v_cndmask_b32_e64 v27, v31, -v16, vcc
	ds_read_b128 v[12:15], v20 offset:16
	ds_read_b128 v[16:19], v20 offset:32
	ds_read_b128 v[20:23], v20 offset:48
	v_fmac_f32_e32 v2, v9, v4
	v_fmac_f32_e32 v2, v32, v5
	s_waitcnt lgkmcnt(2)
	v_fmac_f32_e32 v2, v33, v12
	v_fmac_f32_e32 v2, v34, v13
	v_fmac_f32_e32 v2, v35, v14
	v_fmac_f32_e32 v2, v36, v15
	s_waitcnt lgkmcnt(1)
	v_fmac_f32_e32 v2, v37, v16
	v_fmac_f32_e32 v2, v38, v17
	v_fmac_f32_e32 v2, v39, v18
	s_add_i32 s0, 0, 0x15c00
	v_lshlrev_b32_e32 v3, 2, v1
	v_fmac_f32_e32 v2, v24, v19
	v_add3_u32 v3, s0, v26, v3
	s_waitcnt lgkmcnt(0)
	v_fmac_f32_e32 v2, v20, v25
	v_add_u32_e32 v4, v3, v28
	v_fmac_f32_e32 v2, v21, v30
	v_add_u32_e32 v5, 0x400, v4
	v_fmac_f32_e32 v2, v22, v27
	v_cmp_ne_u32_e32 vcc, 15, v1
	ds_write2_b32 v4, v6, v8 offset1:68
	ds_write2_b32 v4, v9, v32 offset0:136 offset1:204
	ds_write2_b32 v5, v33, v34 offset0:16 offset1:84
	ds_write2_b32 v5, v35, v36 offset0:152 offset1:220
	v_add_u32_e32 v5, 0x800, v4
	v_cndmask_b32_e64 v2, 1.0, -v2, vcc
	ds_write2_b32 v5, v37, v38 offset0:32 offset1:100
	ds_write2_b32 v5, v39, v24 offset0:168 offset1:236
	v_add_u32_e32 v5, 0xc00, v4
	v_add_u32_e32 v3, v3, v29
	ds_write2_b32 v5, v25, v30 offset0:48 offset1:116
	ds_write_b32 v4, v27 offset:3808
	ds_write_b32 v3, v2

; #define LAS __attribute__((address_space(3)))
; __device__ __forceinline__ unsigned cvt_pk_bf16(float lo, float hi) { const bf16x2_t r = __builtin_convertvector((f32x2){lo, hi}, bf16x2_t); return __builtin_bit_cast(unsigned, r); }
; #define MFMA16(a, b, c) __builtin_amdgcn_mfma_f32_16x16x32_bf16(a, b, c, 0, 0, 0)
; __device__ __forceinline__ void gdn_prep_item(LAS unsigned char* lds, int item, int b0, PrepRaw& R, int next_item, const bf16_t* qkv, const float* bg, const float* gconv_w, unsigned char* rec, float* gtarr) {
;     ...
;     {
;         const f32x4 z4 = (f32x4){0.f, 0.f, 0.f, 0.f};
; #pragma unroll
;         for (int rt = 0; rt < 4; ++rt) { f32x4 acc = z4;
; #pragma unroll
;             for (int s = 0; s < 2; ++s) { const bf16x8 tf = *(const LAS bf16x8*)(lds + P2_TB + ((16 * rt + l15) * 72 + 32 * s + 8 * g) * 2), vf = *(const LAS bf16x8*)(lds + P2_VBT + ((16 * wave + l15) * 72 + 32 * s + 8 * g) * 2);
;                 acc = MFMA16(tf, vf, acc); }
;             u32x2 w; w.x = cvt_pk_bf16(acc[0], acc[1]); w.y = cvt_pk_bf16(acc[2], acc[3]);
;             *(u32x2*)(rec + REC_U + ((rt * 8 + wave) * 64 + lane) * 8) = w; }
;         const int rt = wave >> 1;
; #pragma unroll
;         for (int q = 0; q < 2; ++q) { const int s2 = 2 * (wave & 1) + q; f32x4 a0 = z4, a1 = z4;
; #pragma unroll
;             for (int s = 0; s < 2; ++s) { const bf16x8 tf = *(const LAS bf16x8*)(lds + P2_TB + ((16 * rt + l15) * 72 + 32 * s + 8 * g) * 2);
;                 const bf16x8 k0 = *(const LAS bf16x8*)(lds + P2_KBT + ((32 * s2 + l15) * 72 + 32 * s + 8 * g) * 2), k1 = *(const LAS bf16x8*)(lds + P2_KBT + ((32 * s2 + 16 + l15) * 72 + 32 * s + 8 * g) * 2);
;                 a0 = MFMA16(k0, tf, a0); a1 = MFMA16(k1, tf, a1); }
;             *(bf16x8*)(rec + REC_WN + ((rt * 4 + s2) * 64 + lane) * 16) = pack8(-a0, -a1); }
;     }
.LBB0_700:
	s_or_b64 exec, exec, s[0:1]
	s_movk_i32 s8, 0x48
	s_add_u32 s0, s4, 0xe000
	s_addc_u32 s1, s5, 0
	v_mad_u32_u24 v2, v1, s8, v10
	s_add_i32 s9, 0, 0x1a000
	v_lshl_add_u32 v38, v2, 1, s9
	s_waitcnt lgkmcnt(0)
	s_barrier
	ds_read_b128 v[2:5], v38
	v_lshl_or_b32 v9, s20, 4, v1
	v_mad_u64_u32 v[12:13], s[6:7], v9, s8, v[10:11]
	v_lshl_add_u32 v9, v12, 1, 0
	ds_read_b128 v[12:15], v38 offset:64
	ds_read_b128 v[16:19], v9 offset:34816
	ds_read_b128 v[20:23], v9 offset:34880
	s_waitcnt lgkmcnt(1)
	v_mfma_f32_16x16x32_bf16 v[2:5], v[2:5], v[16:19], 0
	ds_read_b128 v[24:27], v38 offset:2304
	v_or_b32_e32 v9, 0x480, v10
	v_lshl_or_b32 v7, s22, 12, v7
	s_waitcnt lgkmcnt(1)
	v_mfma_f32_16x16x32_bf16 v[2:5], v[12:15], v[20:23], v[2:5]
	ds_read_b128 v[12:15], v38 offset:2368
	s_nop 6
	v_cvt_pk_bf16_f32 v28, v2, v3
	v_lshlrev_b32_e32 v2, 3, v101
	v_lshl_or_b32 v36, s20, 9, v2
	v_ashrrev_i32_e32 v37, 31, v36
	v_cvt_pk_bf16_f32 v29, v4, v5
	s_waitcnt lgkmcnt(1)
	v_mfma_f32_16x16x32_bf16 v[2:5], v[24:27], v[16:19], 0
	v_lshl_add_u64 v[24:25], s[0:1], 0, v[36:37]
	global_store_dwordx2 v[24:25], v[28:29], off sc0 sc1
	ds_read_b128 v[24:27], v38 offset:4608
	s_waitcnt lgkmcnt(1)
	v_mfma_f32_16x16x32_bf16 v[2:5], v[12:15], v[20:23], v[2:5]
	ds_read_b128 v[12:15], v38 offset:4672
	v_add_u32_e32 v30, 0x1000, v36
	v_ashrrev_i32_e32 v31, 31, v30
	v_add_u32_e32 v34, 0x2000, v36
	v_ashrrev_i32_e32 v35, 31, v34
	s_nop 2
	v_cvt_pk_bf16_f32 v28, v2, v3
	v_cvt_pk_bf16_f32 v29, v4, v5
	s_waitcnt lgkmcnt(1)
	v_mfma_f32_16x16x32_bf16 v[2:5], v[24:27], v[16:19], 0
	v_lshl_add_u64 v[24:25], s[0:1], 0, v[30:31]
	global_store_dwordx2 v[24:25], v[28:29], off sc0 sc1
	ds_read_b128 v[24:27], v38 offset:6912
	s_waitcnt lgkmcnt(1)
	v_mfma_f32_16x16x32_bf16 v[2:5], v[12:15], v[20:23], v[2:5]
	v_lshl_add_u64 v[34:35], s[0:1], 0, v[34:35]
	v_add_u32_e32 v36, 0x3000, v36
	s_nop 5
	v_cvt_pk_bf16_f32 v32, v2, v3
	v_cvt_pk_bf16_f32 v33, v4, v5
	ds_read_b128 v[2:5], v38 offset:6976
	s_waitcnt lgkmcnt(1)
	v_mfma_f32_16x16x32_bf16 v[12:15], v[24:27], v[16:19], 0
	v_mad_u64_u32 v[16:17], s[6:7], v11, s8, v[10:11]
	v_lshl_or_b32 v24, s23, 6, v1
	v_lshl_add_u32 v11, v16, 1, s9
	v_mad_u32_u24 v16, v24, s8, v10
	v_lshl_add_u32 v37, v16, 1, 0
	v_mad_u32_u24 v28, v24, s8, v9
	ds_read_b128 v[16:19], v37 offset:53248
	ds_read_b128 v[24:27], v11
	v_lshl_add_u32 v39, v28, 1, 0
	ds_read_b128 v[28:31], v39 offset:53248
	s_waitcnt lgkmcnt(3)
	v_mfma_f32_16x16x32_bf16 v[2:5], v[2:5], v[20:23], v[12:15]
	s_nop 2
	ds_read_b128 v[12:15], v11 offset:64
	ds_read_b128 v[20:23], v37 offset:53312
	global_store_dwordx2 v[34:35], v[32:33], off sc0 sc1
	ds_read_b128 v[32:35], v39 offset:53312
	s_waitcnt lgkmcnt(4)
	v_mfma_f32_16x16x32_bf16 v[16:19], v[16:19], v[24:27], 0
	v_ashrrev_i32_e32 v37, 31, v36
	v_cvt_pk_bf16_f32 v38, v2, v3
	v_cvt_pk_bf16_f32 v39, v4, v5
	s_waitcnt lgkmcnt(3)
	v_mfma_f32_16x16x32_bf16 v[28:31], v[28:31], v[24:27], 0
	s_movk_i32 s6, 0x88
	s_waitcnt lgkmcnt(1)
	v_mfma_f32_16x16x32_bf16 v[2:5], v[20:23], v[12:15], v[16:19]
	s_nop 2
	v_lshl_add_u64 v[16:17], s[0:1], 0, v[36:37]
	global_store_dwordx2 v[16:17], v[38:39], off sc0 sc1
	s_waitcnt lgkmcnt(0)
	v_mfma_f32_16x16x32_bf16 v[16:19], v[32:35], v[12:15], v[28:31]
	s_lshl_b32 s0, s23, 1
	s_or_b32 s0, s0, 1
	v_xor_b32_e32 v11, 0x80000000, v5
	v_xor_b32_e32 v28, 0x80000000, v2
	v_xor_b32_e32 v22, 0x80000000, v4
	s_nop 2
	v_xor_b32_e32 v31, 0x80000000, v19
	v_lshl_or_b32 v19, s0, 5, v1
	v_mad_u32_u24 v2, v19, s8, v10
	v_mad_u32_u24 v9, v19, s8, v9
	v_lshl_add_u32 v10, v2, 1, 0
	v_lshl_add_u32 v9, v9, 1, 0
	v_xor_b32_e32 v23, 0x80000000, v3
	ds_read_b128 v[2:5], v10 offset:53248
	ds_read_b128 v[32:35], v10 offset:53312
	v_xor_b32_e32 v40, 0x80000000, v18
	ds_read_b128 v[18:21], v9 offset:53248
	ds_read_b128 v[36:39], v9 offset:53312
	v_xor_b32_e32 v17, 0x80000000, v17
	v_xor_b32_e32 v16, 0x80000000, v16
	s_waitcnt lgkmcnt(3)
	v_mfma_f32_16x16x32_bf16 v[2:5], v[2:5], v[24:27], 0
	v_cvt_pk_bf16_f32 v30, v16, v17
	v_lshl_or_b32 v10, s23, 11, v7
	v_cvt_pk_bf16_f32 v29, v22, v11
	s_waitcnt lgkmcnt(1)
	v_mfma_f32_16x16x32_bf16 v[16:19], v[18:21], v[24:27], 0
	v_ashrrev_i32_e32 v11, 31, v10
	v_cvt_pk_bf16_f32 v28, v28, v23
	v_cvt_pk_bf16_f32 v31, v40, v31
	v_lshl_add_u64 v[10:11], s[4:5], 0, v[10:11]
	v_mfma_f32_16x16x32_bf16 v[2:5], v[32:35], v[12:15], v[2:5]
	global_store_dwordx4 v[10:11], v[28:31], off sc0 sc1
	v_mov_b32_e32 v20, 0x990
	v_mov_b32_e32 v21, 0xa18
	s_waitcnt lgkmcnt(0)
	v_mfma_f32_16x16x32_bf16 v[10:13], v[36:39], v[12:15], v[16:19]
	v_and_b32_e32 v15, 12, v8
	s_nop 1
	v_xor_b32_e32 v5, 0x80000000, v5
	v_xor_b32_e32 v4, 0x80000000, v4
	v_xor_b32_e32 v3, 0x80000000, v3
	v_xor_b32_e32 v2, 0x80000000, v2
	s_nop 0
	v_xor_b32_e32 v11, 0x80000000, v11
	v_xor_b32_e32 v10, 0x80000000, v10
	v_cvt_pk_bf16_f32 v2, v2, v3
	v_cvt_pk_bf16_f32 v3, v4, v5
	v_cvt_pk_bf16_f32 v4, v10, v11
	v_lshl_or_b32 v10, s0, 10, v7
	v_xor_b32_e32 v9, 0x80000000, v13
	v_xor_b32_e32 v12, 0x80000000, v12
	v_ashrrev_i32_e32 v11, 31, v10
	v_cvt_pk_bf16_f32 v5, v12, v9
	v_lshl_add_u64 v[10:11], s[4:5], 0, v[10:11]
	global_store_dwordx4 v[10:11], v[2:5], off sc0 sc1
	v_lshrrev_b32_e32 v11, 1, v99
	v_and_b32_e32 v10, 0x60, v11
	v_ashrrev_i32_e32 v2, 4, v99
	v_and_or_b32 v2, v2, -16, v1
	v_lshl_add_u32 v7, v2, 2, s21
	v_mad_u64_u32 v[2:3], s[8:9], v2, s6, v[10:11]
	v_add_u32_e32 v3, v2, v15
	v_lshl_add_u32 v3, v3, 1, 0
	ds_read_b64 v[4:5], v3
	v_add_u32_e32 v18, 0x200, v99
	v_or_b32_e32 v16, 16, v15
	v_ashrrev_i32_e32 v3, 4, v18
	v_add_u32_e32 v2, v2, v16
	v_and_or_b32 v17, v3, -16, v1
	v_lshl_add_u32 v2, v2, 1, 0
	v_lshl_add_u32 v3, v17, 2, s21
	ds_read_b32 v8, v7
	ds_read_b64 v[12:13], v2
	ds_read_b32 v14, v3
	s_waitcnt lgkmcnt(3)
; #define LAS __attribute__((address_space(3)))
; __device__ __forceinline__ float bf2f(bf16_t b) { return __uint_as_float(((unsigned)b) << 16); }
; __device__ __forceinline__ void gdn_prep_item(LAS unsigned char* lds, int item, int b0, PrepRaw& R, int next_item, const bf16_t* qkv, const float* bg, const float* gconv_w, unsigned char* rec, float* gtarr) {
;     ...
;     for (int q = 0; q < 2; ++q) { const int task = tid + q * NTHREADS, fragi = task >> 6, ln = task & 63, lg = ln >> 4, l = ln & 15;
;         const int rt = fragi >> 2, s2 = fragi & 3, i = 16 * rt + l; const float e = EG[i];
;         const u32x2 lo = *(const LAS u32x2*)(lds + P2_QN + (i * 136 + 32 * s2 + 4 * lg) * 2), hi = *(const LAS u32x2*)(lds + P2_QN + (i * 136 + 32 * s2 + 16 + 4 * lg) * 2);
;         const unsigned vv[4] = {lo.x, lo.y, hi.x, hi.y}; u32x4 w; unsigned ww[4];
; #pragma unroll
;         for (int k2 = 0; k2 < 4; ++k2) ww[k2] = cvt_pk_bf16(__uint_as_float(vv[k2] << 16) * e, __uint_as_float(vv[k2] & 0xffff0000u) * e);
;         w.x = ww[0]; w.y = ww[1]; w.z = ww[2]; w.w = ww[3];
;         *(u32x4*)(rec + REC_QD + (fragi * 64 + ln) * 16) = w; }
; #pragma unroll
;     for (int q = 0; q < 2; ++q) { const int task = tid + q * NTHREADS, fragi = task >> 6, ln = task & 63, lg = ln >> 4, l = ln & 15;
;         const int dt = fragi >> 1, s = fragi & 1, dk = 16 * dt + l; float v[8];
; #pragma unroll
;         for (int j = 0; j < 8; ++j) { const int i = 32 * s + 4 * lg + (j & 3) + 16 * (j >> 2); v[j] = bf2f(*(const LAS bf16_t*)(lds + P2_KN + (i * 136 + dk) * 2)) * DKs[i]; }
;         u32x4 w; w.x = cvt_pk_bf16(v[0], v[1]); w.y = cvt_pk_bf16(v[2], v[3]); w.z = cvt_pk_bf16(v[4], v[5]); w.w = cvt_pk_bf16(v[6], v[7]);
;         *(u32x4*)(rec + REC_KDT + (fragi * 64 + ln) * 16) = w; }
; __device__ __forceinline__ void gdn_all(LAS unsigned char* lds, const XcdBarrier& xbar, const int G, const int bx, unsigned char* ws, float* out, const bf16_t* qkv, const float* bg, const float* gconv_w, ...
;     ...
;         asm volatile("s_waitcnt vmcnt(0)" ::: "memory"); __syncthreads();
;         if (threadIdx.x == 0) { __builtin_amdgcn_fence(__ATOMIC_RELEASE, "agent"); asm volatile("s_waitcnt vmcnt(0)" ::: "memory"); __hip_atomic_fetch_add(late_cnt, 1u, __ATOMIC_RELAXED, __HIP_MEMORY_SCOPE_AGENT); }
	v_lshlrev_b32_e32 v2, 16, v4
	v_and_b32_e32 v3, 0xffff0000, v4
	v_lshlrev_b32_e32 v4, 16, v5
	v_and_b32_e32 v5, 0xffff0000, v5
	s_waitcnt lgkmcnt(2)
	v_pk_mul_f32 v[2:3], v[8:9], v[2:3] op_sel_hi:[0,1]
	v_pk_mul_f32 v[4:5], v[8:9], v[4:5] op_sel_hi:[0,1]
	s_add_u32 s0, s4, 0x4000
	v_cvt_pk_bf16_f32 v2, v2, v3
	v_cvt_pk_bf16_f32 v3, v4, v5
	s_waitcnt lgkmcnt(1)
	v_lshlrev_b32_e32 v4, 16, v12
	v_and_b32_e32 v5, 0xffff0000, v12
	v_lshlrev_b32_e32 v12, 16, v13
	v_and_b32_e32 v13, 0xffff0000, v13
	s_addc_u32 s1, s5, 0
	v_pk_mul_f32 v[4:5], v[8:9], v[4:5] op_sel_hi:[0,1]
	v_pk_mul_f32 v[8:9], v[8:9], v[12:13] op_sel_hi:[0,1]
	v_ashrrev_i32_e32 v7, 31, v6
	v_cvt_pk_bf16_f32 v4, v4, v5
	v_cvt_pk_bf16_f32 v5, v8, v9
	v_lshl_add_u64 v[8:9], s[0:1], 0, v[6:7]
	global_store_dwordx4 v[8:9], v[2:5], off sc0 sc1
	v_mov_b32_e32 v19, 0x908
	v_mov_b32_e32 v13, 0x110
	v_mad_u64_u32 v[2:3], s[8:9], v17, s6, v[10:11]
	v_add_u32_e32 v3, v2, v15
	v_lshl_add_u32 v3, v3, 1, 0
	ds_read_b64 v[4:5], v3
	v_add_u32_e32 v2, v2, v16
	v_and_or_b32 v10, v11, 32, v15
	v_and_or_b32 v11, v98, -16, v1
	v_lshl_add_u32 v2, v2, 1, 0
	v_mad_u32_u24 v3, v10, s6, v11
	v_lshl_add_u32 v3, v3, 1, 0
	ds_read_b64 v[8:9], v2
	ds_read_u16 v12, v3 offset:17408
	s_waitcnt lgkmcnt(2)
	v_lshlrev_b32_e32 v2, 16, v4
	v_and_b32_e32 v3, 0xffff0000, v4
	v_lshlrev_b32_e32 v4, 16, v5
	v_and_b32_e32 v5, 0xffff0000, v5
	v_pk_mul_f32 v[2:3], v[14:15], v[2:3] op_sel_hi:[0,1]
	v_pk_mul_f32 v[4:5], v[14:15], v[4:5] op_sel_hi:[0,1]
	v_cvt_pk_bf16_f32 v2, v2, v3
	v_cvt_pk_bf16_f32 v3, v4, v5
	s_waitcnt lgkmcnt(1)
	v_lshlrev_b32_e32 v4, 16, v8
	v_and_b32_e32 v5, 0xffff0000, v8
	v_lshlrev_b32_e32 v8, 16, v9
	v_and_b32_e32 v9, 0xffff0000, v9
	v_lshlrev_b32_e32 v16, 4, v18
	v_pk_mul_f32 v[4:5], v[14:15], v[4:5] op_sel_hi:[0,1]
	v_pk_mul_f32 v[8:9], v[14:15], v[8:9] op_sel_hi:[0,1]
	v_ashrrev_i32_e32 v17, 31, v16
	v_cvt_pk_bf16_f32 v4, v4, v5
	v_cvt_pk_bf16_f32 v5, v8, v9
	v_lshl_add_u64 v[8:9], s[0:1], 0, v[16:17]
	v_mov_b32_e32 v14, 0x198
	global_store_dwordx4 v[8:9], v[2:5], off sc0 sc1
	v_mad_u32_u24 v22, v10, s6, s6
	v_mad_u32_u24 v24, v10, s6, v14
	v_lshl_add_u32 v2, v10, 2, 0
	v_mov_b32_e32 v15, 0x880
	v_mad_u32_u24 v26, v10, s6, v19
	v_mad_u32_u24 v27, v10, s6, v20
	v_ashrrev_i32_e32 v18, 3, v18
	v_add_u32_e32 v8, 0x1d300, v2
	v_add_u32_e32 v2, v22, v11
	v_mad_u32_u24 v23, v10, s6, v13
	v_add_u32_e32 v14, v24, v11
	v_mad_u32_u24 v25, v10, s6, v15
	v_add_u32_e32 v19, v26, v11
	v_add_u32_e32 v20, v27, v11
	v_mad_u32_u24 v28, v10, s6, v21
	v_and_or_b32 v1, v18, -16, v1
	v_lshl_add_u32 v9, v2, 1, 0
	v_add_u32_e32 v13, v23, v11
	v_lshl_add_u32 v14, v14, 1, 0
	v_add_u32_e32 v15, v25, v11
	v_lshl_add_u32 v19, v19, 1, 0
	v_lshl_add_u32 v20, v20, 1, 0
	v_add_u32_e32 v11, v28, v11
	v_mad_u32_u24 v10, v10, s6, v1
	ds_read_b128 v[2:5], v8
	v_lshl_add_u32 v13, v13, 1, 0
	v_lshl_add_u32 v15, v15, 1, 0
	v_lshl_add_u32 v11, v11, 1, 0
	v_lshl_add_u32 v10, v10, 1, 0
	ds_read_u16 v9, v9 offset:17408
	ds_read_u16 v18, v13 offset:17408
	ds_read_u16 v14, v14 offset:17408
	ds_read_u16 v21, v15 offset:17408
	ds_read_u16 v19, v19 offset:17408
	ds_read_u16 v20, v20 offset:17408
	ds_read_u16 v29, v11 offset:17408
	ds_read_u16 v30, v10 offset:17408
	s_waitcnt lgkmcnt(7)
	v_lshlrev_b32_e32 v13, 16, v9
	ds_read_b128 v[8:11], v8 offset:64
	s_add_u32 s0, s4, 0x8000
	v_lshlrev_b32_e32 v12, 16, v12
	s_waitcnt lgkmcnt(6)
	v_lshlrev_b32_e32 v15, 16, v14
	v_lshlrev_b32_e32 v14, 16, v18
	s_waitcnt lgkmcnt(4)
	v_lshlrev_b32_e32 v19, 16, v19
	v_lshlrev_b32_e32 v18, 16, v21
	s_waitcnt lgkmcnt(2)
	v_lshlrev_b32_e32 v21, 16, v29
	v_lshlrev_b32_e32 v20, 16, v20
	s_addc_u32 s1, s5, 0
	v_pk_mul_f32 v[12:13], v[2:3], v[12:13]
	v_pk_mul_f32 v[14:15], v[4:5], v[14:15]
	s_waitcnt lgkmcnt(0)
	v_pk_mul_f32 v[18:19], v[8:9], v[18:19]
	v_pk_mul_f32 v[20:21], v[10:11], v[20:21]
	v_cvt_pk_bf16_f32 v12, v12, v13
	v_cvt_pk_bf16_f32 v13, v14, v15
	v_cvt_pk_bf16_f32 v14, v18, v19
	v_cvt_pk_bf16_f32 v15, v20, v21
	v_lshl_add_u64 v[6:7], s[0:1], 0, v[6:7]
	global_store_dwordx4 v[6:7], v[12:15], off sc0 sc1
	v_add_u32_e32 v6, v22, v1
	v_add_u32_e32 v7, v23, v1
	v_add_u32_e32 v12, v24, v1
	v_add_u32_e32 v13, v25, v1
	v_add_u32_e32 v14, v26, v1
	v_add_u32_e32 v15, v27, v1
	v_add_u32_e32 v1, v28, v1
	v_lshl_add_u32 v6, v6, 1, 0
	v_lshl_add_u32 v12, v12, 1, 0
	v_lshl_add_u32 v13, v13, 1, 0
	v_lshl_add_u32 v14, v14, 1, 0
	v_lshl_add_u32 v15, v15, 1, 0
	v_lshl_add_u32 v1, v1, 1, 0
	v_lshl_add_u32 v7, v7, 1, 0
	ds_read_u16 v6, v6 offset:17408
	ds_read_u16 v18, v7 offset:17408
	ds_read_u16 v12, v12 offset:17408
	ds_read_u16 v13, v13 offset:17408
	ds_read_u16 v14, v14 offset:17408
	ds_read_u16 v15, v15 offset:17408
	ds_read_u16 v1, v1 offset:17408
	s_waitcnt lgkmcnt(6)
	v_lshlrev_b32_e32 v7, 16, v6
	v_lshlrev_b32_e32 v6, 16, v30
	v_pk_mul_f32 v[2:3], v[2:3], v[6:7]
	s_waitcnt lgkmcnt(4)
	v_lshlrev_b32_e32 v7, 16, v12
	v_lshlrev_b32_e32 v6, 16, v18
	v_pk_mul_f32 v[4:5], v[4:5], v[6:7]
	s_waitcnt lgkmcnt(2)
	v_lshlrev_b32_e32 v7, 16, v14
	v_lshlrev_b32_e32 v6, 16, v13
	v_pk_mul_f32 v[6:7], v[8:9], v[6:7]
	s_waitcnt lgkmcnt(0)
	v_lshlrev_b32_e32 v9, 16, v1
	v_lshlrev_b32_e32 v8, 16, v15
	v_pk_mul_f32 v[8:9], v[10:11], v[8:9]
	v_cvt_pk_bf16_f32 v2, v2, v3
	v_cvt_pk_bf16_f32 v3, v4, v5
	v_cvt_pk_bf16_f32 v4, v6, v7
	v_cvt_pk_bf16_f32 v5, v8, v9
	v_lshl_add_u64 v[6:7], s[0:1], 0, v[16:17]
	global_store_dwordx4 v[6:7], v[2:5], off sc0 sc1
	s_barrier
	s_waitcnt vmcnt(0)
	s_barrier
	s_and_saveexec_b64 s[0:1], s[66:67]
	s_cbranch_execz .LBB0_703
	s_mov_b64 s[4:5], exec
	v_mbcnt_lo_u32_b32 v1, s4, 0
	s_nop 0
	s_waitcnt vmcnt(0)
	s_waitcnt vmcnt(0)
	v_mbcnt_hi_u32_b32 v1, s5, v1
	v_cmp_eq_u32_e32 vcc, 0, v1
	s_and_b64 s[6:7], exec, vcc
	s_mov_b64 exec, s[6:7]
	s_cbranch_execz .LBB0_703
	s_bcnt1_i32_b64 s4, s[4:5]
	v_mov_b32_e32 v1, s99
	v_lshlrev_b32_e32 v1, 2, v1
	v_mov_b32_e32 v2, s4
	global_atomic_add v1, v2, s[14:15]
.LBB0_703:
	s_or_b64 exec, exec, s[0:1]
	s_add_i32 s99, s99, 1
	s_cmp_lt_u32 s99, 2
	s_cbranch_scc1 .Llt_loop

; #define LAS __attribute__((address_space(3)))
; __device__ __forceinline__ float bf2f(bf16_t b) { return __uint_as_float(((unsigned)b) << 16); }
; __device__ __forceinline__ unsigned cvt_pk_bf16(float lo, float hi) { const bf16x2_t r = __builtin_convertvector((f32x2){lo, hi}, bf16x2_t); return __builtin_bit_cast(unsigned, r); }
; __device__ __forceinline__ void gdn_sample_item(LAS unsigned char* lds, int item, const bf16_t* qkv, const float* bg, const float* gconv_w, const float* st_gconv, const float* st_grec, bf16_t* zb, const float* gnorm_w, float* srec) {
;     ...
; #pragma unroll
;     for (int cc = 0; cc < 4; ++cc)
; #pragma unroll
;         for (int j = 0; j < 8; ++j) Sst[(8 * dki + j) * 132 + cq + 32 * cc] = Sr[cc][j];
;     __syncthreads();
;     { const int tt = wave; const float o0 = os[tt * 128 + lane], o1 = os[tt * 128 + 64 + lane];
;       const float rstd = rsqrtf(wave_sum(o0 * o0 + o1 * o1) * (1.f / DV) + EPS);
;       bf16_t* zr = zb + (size_t)(rowbase + tt) * D + h * 128;
;       const float z0 = bf2f(zr[lane]), z1 = bf2f(zr[64 + lane]);
;       zr[lane] = (bf16_t)(cvt_pk_bf16(o0 * rstd * z0, 0.f) & 0xffffu); zr[64 + lane] = (bf16_t)(cvt_pk_bf16(o1 * rstd * z1, 0.f) & 0xffffu); }
;     float* So = srec + ((size_t)sb * NH + h) * DK * DV;
; #pragma unroll
;     for (int rr = 0; rr < 8; ++rr) { const int dk = (tid >> 5) + 16 * rr, c4 = 4 * (tid & 31); __builtin_nontemporal_store(*(const LAS f32x4*)(Sst + dk * 132 + c4), (f32x4*)(So + (size_t)dk * DV + c4)); }
.LBB0_707:
	v_add_u32_e32 v2, v78, v79
	v_add_u32_e32 v3, 0x4000, v2
	v_add_u32_e32 v5, 0x4400, v2
	v_add_u32_e32 v6, 0x4800, v2
	v_add_u32_e32 v7, 0x4c00, v2
	s_ashr_i32 s0, s34, 6
	ds_write2_b32 v3, v52, v36 offset0:32 offset1:64
	ds_write2_b32 v3, v53, v37 offset0:164 offset1:196
	ds_write2_b32 v5, v54, v38 offset0:40 offset1:72
	ds_write2_b32 v5, v55, v39 offset0:172 offset1:204
	ds_write2_b32 v6, v58, v40 offset0:48 offset1:80
	ds_write2_b32 v6, v59, v41 offset0:180 offset1:212
	ds_write2_b32 v7, v64, v44 offset0:56 offset1:88
	ds_write2_b32 v7, v65, v45 offset0:188 offset1:220
	ds_write2_b32 v3, v66, v42 offset0:96 offset1:128
	v_add_u32_e32 v3, 0x4200, v2
	ds_write2_b32 v3, v67, v43 offset0:100 offset1:132
	ds_write2_b32 v5, v62, v46 offset0:104 offset1:136
	v_add_u32_e32 v3, 0x4600, v2
	s_lshl_b32 s6, s0, 9
	v_and_b32_e32 v4, 63, v77
	ds_write2_b32 v3, v63, v47 offset0:108 offset1:140
	ds_write2_b32 v6, v60, v48 offset0:112 offset1:144
	v_add_u32_e32 v3, 0x4a00, v2
	v_add_u32_e32 v2, 0x4e00, v2
	s_add_i32 s6, s6, 0
	ds_write2_b32 v3, v61, v49 offset0:116 offset1:148
	ds_write2_b32 v7, v56, v50 offset0:120 offset1:152
	ds_write2_b32 v2, v57, v51 offset0:124 offset1:156
	v_lshl_add_u32 v2, v4, 2, s6
	s_add_i32 s6, s0, s31
	s_ashr_i32 s7, s6, 31
	s_lshl_b64 s[6:7], s[6:7], 11
	s_add_u32 s0, s70, s6
	s_addc_u32 s7, s71, s7
	s_lshl_b32 s6, s30, 8
	s_add_u32 s6, s0, s6
	s_addc_u32 s7, s7, 0
	v_lshlrev_b32_e32 v6, 1, v4
	s_waitcnt lgkmcnt(0)
	s_barrier
	ds_read2st64_b32 v[2:3], v2 offset0:48 offset1:49
	global_load_ushort v7, v6, s[6:7]
	global_load_ushort v8, v6, s[6:7] offset:128
	v_xor_b32_e32 v9, 1, v1
	s_add_u32 s4, s23, s4
	s_addc_u32 s5, s24, s5
	s_waitcnt lgkmcnt(0)
	v_pk_mul_f32 v[4:5], v[2:3], v[2:3]
	v_lshl_add_u64 v[14:15], s[4:5], 0, v[18:19]
	v_add_f32_e32 v4, v4, v5
	v_and_b32_e32 v5, 64, v1
	v_add_u32_e32 v5, 64, v5
	v_cmp_lt_i32_e32 vcc, v9, v5
	v_lshl_add_u64 v[10:11], v[14:15], 0, v[20:21]
	v_lshl_add_u64 v[16:17], v[14:15], 0, v[30:31]
	v_cndmask_b32_e32 v9, v1, v9, vcc
	v_lshlrev_b32_e32 v9, 2, v9
	ds_bpermute_b32 v9, v9, v4
	s_add_i32 s22, s25, s22
	s_cmpk_lt_i32 s22, 0x400
	s_waitcnt lgkmcnt(0)
	v_add_f32_e32 v4, v4, v9
	v_xor_b32_e32 v9, 2, v1
	v_cmp_lt_i32_e32 vcc, v9, v5
	s_nop 1
	v_cndmask_b32_e32 v9, v1, v9, vcc
	v_lshlrev_b32_e32 v9, 2, v9
	ds_bpermute_b32 v9, v9, v4
	s_waitcnt lgkmcnt(0)
	v_add_f32_e32 v4, v4, v9
	v_xor_b32_e32 v9, 4, v1
	v_cmp_lt_i32_e32 vcc, v9, v5
	s_nop 1
	v_cndmask_b32_e32 v9, v1, v9, vcc
	v_lshlrev_b32_e32 v9, 2, v9
	ds_bpermute_b32 v9, v9, v4
	s_waitcnt lgkmcnt(0)
	v_add_f32_e32 v4, v4, v9
	v_xor_b32_e32 v9, 8, v1
	v_cmp_lt_i32_e32 vcc, v9, v5
	s_nop 1
	v_cndmask_b32_e32 v9, v1, v9, vcc
	v_lshlrev_b32_e32 v9, 2, v9
	ds_bpermute_b32 v9, v9, v4
	s_waitcnt lgkmcnt(0)
	v_add_f32_e32 v4, v4, v9
	v_xor_b32_e32 v9, 16, v1
	v_cmp_lt_i32_e32 vcc, v9, v5
	s_nop 1
	v_cndmask_b32_e32 v9, v1, v9, vcc
	v_lshlrev_b32_e32 v9, 2, v9
	ds_bpermute_b32 v9, v9, v4
	s_waitcnt lgkmcnt(0)
	v_add_f32_e32 v4, v4, v9
	v_xor_b32_e32 v9, 32, v1
	v_cmp_lt_i32_e32 vcc, v9, v5
	s_nop 1
	v_cndmask_b32_e32 v5, v1, v9, vcc
	v_lshlrev_b32_e32 v5, 2, v5
	ds_bpermute_b32 v5, v5, v4
	s_waitcnt lgkmcnt(0)
	v_add_f32_e32 v4, v4, v5
	v_fmamk_f32 v4, v4, 0x3c000000, v72
	v_mul_f32_e32 v5, 0x4b800000, v4
	v_cmp_gt_f32_e32 vcc, s28, v4
	s_nop 1
	v_cndmask_b32_e32 v4, v4, v5, vcc
	v_rsq_f32_e32 v4, v4
	s_nop 0
	v_mul_f32_e32 v5, 0x45800000, v4
	v_cndmask_b32_e32 v4, v4, v5, vcc
	s_waitcnt vmcnt(1)
	v_lshlrev_b32_e32 v5, 16, v7
	v_mul_f32_e32 v2, v2, v4
	v_mul_f32_e32 v2, v2, v5
	v_cvt_pk_bf16_f32 v2, v2, s0
	s_waitcnt vmcnt(0)
	v_lshlrev_b32_e32 v7, 16, v8
	global_store_short v6, v2, s[6:7]
	v_mul_f32_e32 v2, v3, v4
	v_mul_f32_e32 v2, v2, v7
	v_cvt_pk_bf16_f32 v2, v2, s0
	global_store_short v6, v2, s[6:7] offset:128
	ds_read_b128 v[2:5], v76 offset:16512
	ds_read_b128 v[6:9], v76 offset:17040
	s_waitcnt lgkmcnt(1)
	global_store_dwordx4 v[10:11], v[2:5], off nt
	ds_read_b128 v[2:5], v76 offset:17568
	v_lshl_add_u64 v[10:11], v[14:15], 0, v[22:23]
	s_waitcnt lgkmcnt(1)
	global_store_dwordx4 v[10:11], v[6:9], off nt
	ds_read_b128 v[6:9], v76 offset:18096
	v_lshl_add_u64 v[10:11], v[14:15], 0, v[24:25]
	s_waitcnt lgkmcnt(1)
	global_store_dwordx4 v[10:11], v[2:5], off nt
	ds_read_b128 v[2:5], v76 offset:18624
	v_lshl_add_u64 v[10:11], v[14:15], 0, v[26:27]
	s_waitcnt lgkmcnt(1)
	global_store_dwordx4 v[10:11], v[6:9], off nt
	v_lshl_add_u64 v[10:11], v[14:15], 0, v[28:29]
	ds_read_b128 v[6:9], v76 offset:19152
	s_waitcnt lgkmcnt(1)
	global_store_dwordx4 v[10:11], v[2:5], off nt
	ds_read_b128 v[2:5], v76 offset:19680
	ds_read_b128 v[10:13], v76 offset:20208
	s_waitcnt lgkmcnt(2)
	global_store_dwordx4 v[16:17], v[6:9], off nt
	s_nop 1
	v_lshl_add_u64 v[6:7], v[14:15], 0, v[32:33]
	s_waitcnt lgkmcnt(1)
	global_store_dwordx4 v[6:7], v[2:5], off nt
	s_nop 1
	v_lshl_add_u64 v[2:3], v[14:15], 0, v[34:35]
	s_waitcnt lgkmcnt(0)
	global_store_dwordx4 v[2:3], v[10:13], off nt
	s_barrier
	s_cbranch_scc0 .LBB0_737
; #define LAS __attribute__((address_space(3)))
; __device__ __forceinline__ void gdn_sample_item(LAS unsigned char* lds, int item, const bf16_t* qkv, const float* bg, const float* gconv_w, const float* st_gconv, const float* st_grec, bf16_t* zb, const float* gnorm_w, float* srec) {
;     ...
;     const float* S0 = st_grec + ((size_t)sb * NH + h) * DK * DV;
; #pragma unroll
;     for (int rr = 0; rr < 8; ++rr) { const int dk = (tid >> 5) + 16 * rr, c4 = 4 * (tid & 31); *(LAS f32x4*)(Sst + dk * 132 + c4) = __builtin_nontemporal_load((const f32x4*)(S0 + (size_t)dk * DV + c4)); }
;     for (int task = tid; task < 768; task += NTHREADS) { const int ch = task % 384, half = task / 384, part = ch >> 7, colq = part * 1024 + h * 128 + (ch & 127);
.LBB0_708:
	s_ashr_i32 s8, s22, 3
	s_and_b32 s30, s22, 7
	s_ashr_i32 s9, s8, 31
	s_lshl_b64 s[4:5], s[8:9], 17
	s_lshl_b32 s0, s30, 14
	v_mov_b32_e32 v77, v0
	s_or_b32 s4, s4, s0
	v_readlane_b32 s40, v245, 3
	s_and_b32 s37, s22, -8
	s_lshl_b64 s[4:5], s[4:5], 2
	v_readlane_b32 s46, v245, 9
	v_lshlrev_b32_e32 v2, 2, v77
	v_readlane_b32 s47, v245, 10
	s_add_u32 s6, s46, s4
	v_ashrrev_i32_e32 v52, 5, v77
	v_and_b32_e32 v2, 0x7c, v2
	s_addc_u32 s7, s47, s5
	v_lshlrev_b32_e32 v18, 2, v2
	v_ashrrev_i32_e32 v53, 31, v52
	v_lshl_add_u64 v[44:45], s[6:7], 0, v[18:19]
	v_lshlrev_b64 v[20:21], 12, v[52:53]
	s_mov_b64 s[6:7], 0x200
	v_lshl_add_u64 v[22:23], v[20:21], 0, s[6:7]
	s_mov_b64 s[6:7], 0x400
	v_lshl_add_u64 v[24:25], v[20:21], 0, s[6:7]
	s_mov_b64 s[6:7], 0x600
	v_lshl_add_u64 v[26:27], v[20:21], 0, s[6:7]
	s_mov_b64 s[6:7], 0x800
	v_lshl_add_u64 v[28:29], v[20:21], 0, s[6:7]
	s_mov_b64 s[6:7], 0xa00
	v_lshl_add_u64 v[2:3], v[44:45], 0, v[20:21]
	v_lshl_add_u64 v[6:7], v[44:45], 0, v[22:23]
	v_lshl_add_u64 v[10:11], v[44:45], 0, v[24:25]
	v_lshl_add_u64 v[14:15], v[44:45], 0, v[26:27]
	v_lshl_add_u64 v[32:33], v[44:45], 0, v[28:29]
	v_lshl_add_u64 v[30:31], v[20:21], 0, s[6:7]
	s_mov_b64 s[6:7], 0xc00
	global_load_dwordx4 v[2:5], v[2:3], off nt
	s_nop 0
	global_load_dwordx4 v[6:9], v[6:7], off nt
	s_nop 0
	global_load_dwordx4 v[10:13], v[10:11], off nt
	s_nop 0
	global_load_dwordx4 v[14:17], v[14:15], off nt
	v_lshl_add_u64 v[34:35], v[44:45], 0, v[30:31]
	global_load_dwordx4 v[36:39], v[32:33], off nt
	global_load_dwordx4 v[40:43], v[34:35], off nt
	v_lshl_add_u64 v[32:33], v[20:21], 0, s[6:7]
	s_mov_b64 s[6:7], 0xe00
	v_lshl_add_u64 v[34:35], v[20:21], 0, s[6:7]
	v_lshl_add_u64 v[46:47], v[44:45], 0, v[32:33]
	v_lshl_add_u64 v[48:49], v[44:45], 0, v[34:35]
	global_load_dwordx4 v[44:47], v[46:47], off nt
	s_nop 0
	global_load_dwordx4 v[48:51], v[48:49], off nt
	s_movk_i32 s0, 0x1080
	v_and_b32_e32 v90, 7, v52
	v_lshlrev_b32_e32 v90, 4, v90
	v_mul_lo_u32 v52, v52, s0
	s_movk_i32 s6, 0x300
	v_add_u32_e32 v53, 0x6300, v52
	v_xor_b32_e32 v54, v90, v18
	v_readfirstlane_b32 s34, v77
	v_add_u32_e32 v76, v54, v52
	v_add_u32_e32 v75, v54, v53
	s_add_i32 s31, s37, 0x4080
	v_cmp_gt_i32_e32 vcc, s6, v77
	v_readlane_b32 s41, v245, 4
	v_readlane_b32 s42, v245, 5
	v_readlane_b32 s43, v245, 6
	v_readlane_b32 s44, v245, 7
	v_readlane_b32 s45, v245, 8
	v_readlane_b32 s48, v245, 11
	v_readlane_b32 s49, v245, 12
	v_readlane_b32 s50, v245, 13
	v_readlane_b32 s51, v245, 14
	v_readlane_b32 s52, v245, 15
	v_readlane_b32 s53, v245, 16
	v_readlane_b32 s54, v245, 17
	v_readlane_b32 s55, v245, 18
	s_waitcnt vmcnt(7)
	ds_write_b128 v76, v[2:5] offset:16512
	s_waitcnt vmcnt(6)
	ds_write_b128 v76, v[6:9] offset:17040
	s_waitcnt vmcnt(5)
	ds_write_b128 v76, v[10:13] offset:17568
	s_waitcnt vmcnt(4)
	ds_write_b128 v76, v[14:17] offset:18096
	s_waitcnt vmcnt(3)
	ds_write_b128 v76, v[36:39] offset:18624
	s_waitcnt vmcnt(2)
	ds_write_b128 v76, v[40:43] offset:19152
	s_waitcnt vmcnt(1)
	ds_write_b128 v76, v[44:47] offset:19680
	s_waitcnt vmcnt(0)
	ds_write_b128 v76, v[48:51] offset:20208
	s_and_saveexec_b64 s[6:7], vcc
	s_cbranch_execz .LBB0_723
	s_lshl_b32 s0, s30, 7
	s_mul_hi_i32 s9, s8, 3
	s_mul_i32 s8, s8, 3
	s_add_i32 s35, s37, 0x407d
	s_add_i32 s36, s37, 0x407e
	s_addk_i32 s37, 0x407f
	s_mov_b64 s[18:19], 0
	v_mov_b32_e32 v12, v77
	s_branch .LBB0_711

; __device__ __forceinline__ void gdn_sample_item(LAS unsigned char* lds, int item, const bf16_t* qkv, const float* bg, const float* gconv_w, const float* st_gconv, const float* st_grec, bf16_t* zb, const float* gnorm_w, float* srec) {
;     ...
;     float Sr[4][8];
; #pragma unroll
;     for (int cc = 0; cc < 4; ++cc)
; #pragma unroll
;         for (int j = 0; j < 8; ++j) Sr[cc][j] = Sst[(8 * dki + j) * 132 + cq + 32 * cc];
;     __syncthreads();
.LBB0_727:
	s_or_b64 exec, exec, s[6:7]
	v_lshlrev_b32_e32 v3, 2, v3
	v_and_b32_e32 v90, 7, v2
	v_lshlrev_b32_e32 v90, 4, v90
	v_xor_b32_e32 v78, v90, v3
	s_movk_i32 s0, 0x1080
	v_mad_u32_u24 v50, v2, s0, v78
	v_add_u32_e32 v12, 0x4000, v50
	v_add_u32_e32 v14, 0x4400, v50
	v_add_u32_e32 v16, 0x4800, v50
	v_add_u32_e32 v51, 0x4c00, v50
	v_add_u32_e32 v15, 0x4200, v50
	v_add_u32_e32 v17, 0x4600, v50
	v_add_u32_e32 v48, 0x4a00, v50
	v_add_u32_e32 v50, 0x4e00, v50
	ds_read2_b32 v[4:5], v12 offset0:32 offset1:64
	ds_read2_b32 v[36:37], v12 offset0:164 offset1:196
	ds_read2_b32 v[6:7], v14 offset0:40 offset1:72
	ds_read2_b32 v[38:39], v14 offset0:172 offset1:204
	ds_read2_b32 v[8:9], v16 offset0:48 offset1:80
	ds_read2_b32 v[40:41], v16 offset0:180 offset1:212
	ds_read2_b32 v[10:11], v51 offset0:56 offset1:88
	ds_read2_b32 v[44:45], v51 offset0:188 offset1:220
	ds_read2_b32 v[12:13], v12 offset0:96 offset1:128
	ds_read2_b32 v[42:43], v15 offset0:100 offset1:132
	ds_read2_b32 v[14:15], v14 offset0:104 offset1:136
	ds_read2_b32 v[46:47], v17 offset0:108 offset1:140
	ds_read2_b32 v[16:17], v16 offset0:112 offset1:144
	ds_read2_b32 v[48:49], v48 offset0:116 offset1:148
	ds_read2_b32 v[68:69], v51 offset0:120 offset1:152
	ds_read2_b32 v[50:51], v50 offset0:124 offset1:156
	s_add_i32 s6, 0, 0x2000
	v_mul_u32_u24_e32 v79, 0x1080, v2
	v_lshl_add_u32 v80, v2, 5, 0
	s_mov_b32 s0, 0
	v_cmp_eq_u32_e32 vcc, 0, v2
	v_add_u32_e32 v81, s6, v3
	s_mov_b32 s8, s29
	s_waitcnt lgkmcnt(9)
	v_mov_b32_e32 v64, v10
	s_waitcnt lgkmcnt(8)
	v_mov_b32_e32 v65, v44
	v_mov_b32_e32 v58, v8
	v_mov_b32_e32 v59, v40
	v_mov_b32_e32 v54, v6
	v_mov_b32_e32 v55, v38
	v_mov_b32_e32 v52, v4
	v_mov_b32_e32 v53, v36
	v_mov_b32_e32 v44, v11
	v_mov_b32_e32 v40, v9
	v_mov_b32_e32 v38, v7
	v_mov_b32_e32 v36, v5
	s_waitcnt lgkmcnt(1)
	v_mov_b32_e32 v56, v68
	s_waitcnt lgkmcnt(0)
	v_mov_b32_e32 v57, v50
	v_mov_b32_e32 v60, v16
	v_mov_b32_e32 v61, v48
	v_mov_b32_e32 v62, v14
	v_mov_b32_e32 v63, v46
	v_mov_b32_e32 v66, v12
	v_mov_b32_e32 v67, v42
	v_mov_b32_e32 v50, v69
	v_mov_b32_e32 v48, v17
	v_mov_b32_e32 v46, v15
	v_mov_b32_e32 v42, v13
	s_barrier
	s_branch .LBB0_729

; template <class RecFn>
; __device__ __forceinline__ void gdn_scan(LAS unsigned char* lds, int bh, int b0, RecFn rec_of, const float* gtarr, bf16_t* zb, const float* gnorm_w, float* Sout, const unsigned* late_cnt, unsigned late_need, int cwait) {
;     ...
;     if (cwait == 0) late_wait();
; __device__ __forceinline__ void gdn_all(LAS unsigned char* lds, const XcdBarrier& xbar, const int G, const int bx, unsigned char* ws, float* out, const bf16_t* qkv, const float* bg, const float* gconv_w, ...
;     ...
;         if (bx < 64) { const int cw = nfull * G / 8 - (bx >> 3) * NCHUNK;
;             gdn_scan(lds, bx, 0, rec_of, gtarr, zb, gnorm_w, out + O_PREC + (size_t)bx * DK * DV, late_cnt, (unsigned)nlate, nlate > 0 ? (cw < 0 ? 0 : cw) : NCHUNK + 1); }
.LBB0_741:
	s_or_b64 exec, exec, s[0:1]
	s_ashr_i32 s0, s3, 31
	s_lshr_b32 s0, s0, 29
	s_add_i32 s3, s3, s0
	s_ashr_i32 s24, s94, 3
	s_ashr_i32 s0, s3, 3
	s_mul_i32 s1, s24, 0xffffffdf
	s_add_i32 s0, s0, s1
	s_max_i32 s3, s0, 0
	s_and_b64 s[0:1], exec, s[16:17]
	s_cselect_b32 s3, s3, 34
	s_mov_b32 s3, 28
	s_mov_b32 s2, 0xc0
	s_cmp_lg_u32 s3, 0
	s_cbranch_scc1 .LBB0_758
	s_and_saveexec_b64 s[0:1], s[66:67]
	s_cbranch_execz .LBB0_757
	v_mov_b32_e32 v1, 0
	global_load_dword v3, v1, s[14:15] sc1
	s_waitcnt vmcnt(0)
	v_cmp_le_u32_e32 vcc, s2, v3
	s_cbranch_vccnz .LBB0_756
	s_mov_b32 s6, 0x100008
	s_branch .LBB0_747

; template <class RecFn>
; __device__ __forceinline__ void gdn_scan(LAS unsigned char* lds, int bh, int b0, RecFn rec_of, const float* gtarr, bf16_t* zb, const float* gnorm_w, float* Sout, const unsigned* late_cnt, unsigned late_need, int cwait) {
;     ...
;     auto late_wait = [&]() {
;         if (threadIdx.x == 0) { unsigned polls = 0;
;             while (__hip_atomic_load(late_cnt, __ATOMIC_RELAXED, __HIP_MEMORY_SCOPE_AGENT) < late_need) { if (++polls > (1u << 20)) break; __builtin_amdgcn_s_sleep(8); }
;             __builtin_amdgcn_fence(__ATOMIC_ACQUIRE, "agent"); asm volatile("s_waitcnt vmcnt(0)" ::: "memory"); }
;         __syncthreads(); };
;     ...
;         if (c + 1 == cwait) late_wait();
.LBB0_779:
	s_or_b64 exec, exec, s[22:23]
	s_barrier
	s_add_i32 s3, s3, 3
	s_add_u32 s14, s14, 4
	s_addc_u32 s15, s15, 0
	s_mov_b32 s2, 0x80
	s_cmpk_gt_u32 s3, 0x20
	s_cselect_b32 s3, 0x63, s3
